# fuse next rmsnorm+adaLN modulate into residual GEMM epilogue (4-WG row-sum exchange); norm phases keep sample rows only
# speedup vs baseline: 1.0950x; 1.0088x over previous
.Lup_f_notail:
	s_add_u32 s30, s10, 0x6000000
	s_addc_u32 s31, s11, 0
	v_lshlrev_b32_e32 v228, 1, v224
	v_mov_b32_e32 v229, 0
	v_lshl_add_u64 v[228:229], s[30:31], 0, v[228:229]
	s_lshr_b32 s27, s19, 6
	s_mul_i32 s27, s27, 0xb000
	v_cvt_pk_bf16_f32 v242, v130, v131
	v_cvt_pk_bf16_f32 v243, v132, v133
	v_cvt_pk_bf16_f32 v244, v126, v127
	v_cvt_pk_bf16_f32 v245, v128, v129
	v_cvt_pk_bf16_f32 v246, v122, v123
	v_cvt_pk_bf16_f32 v247, v124, v125
	v_cvt_pk_bf16_f32 v248, v118, v119
	v_cvt_pk_bf16_f32 v249, v120, v121
	s_mov_b32 exec_lo, 0x00010001
	s_mov_b32 exec_hi, 0x00010001
	s_add_u32 s28, s27, 0x0
	s_mov_b32 s29, 0
	v_lshl_add_u64 v[146:147], v[228:229], 0, s[28:29]
	global_store_dwordx4 v[146:147], v[242:245], off
	s_add_u32 s28, s28, 0x1600
	v_lshl_add_u64 v[146:147], v[228:229], 0, s[28:29]
	global_store_dwordx4 v[146:147], v[246:249], off
	v_cvt_pk_bf16_f32 v242, v114, v115
	v_cvt_pk_bf16_f32 v243, v116, v117
	v_cvt_pk_bf16_f32 v244, v110, v111
	v_cvt_pk_bf16_f32 v245, v112, v113
	v_cvt_pk_bf16_f32 v246, v106, v107
	v_cvt_pk_bf16_f32 v247, v108, v109
	v_cvt_pk_bf16_f32 v248, v102, v103
	v_cvt_pk_bf16_f32 v249, v104, v105
	s_add_u32 s28, s27, 0x2c00
	s_mov_b32 s29, 0
	v_lshl_add_u64 v[146:147], v[228:229], 0, s[28:29]
	global_store_dwordx4 v[146:147], v[242:245], off
	s_add_u32 s28, s28, 0x1600
	v_lshl_add_u64 v[146:147], v[228:229], 0, s[28:29]
	global_store_dwordx4 v[146:147], v[246:249], off
	s_mov_b64 exec, -1
	v_cvt_pk_bf16_f32 v242, v98, v99
	v_cvt_pk_bf16_f32 v243, v100, v101
	v_cvt_pk_bf16_f32 v244, v94, v95
	v_cvt_pk_bf16_f32 v245, v96, v97
	v_cvt_pk_bf16_f32 v246, v90, v91
	v_cvt_pk_bf16_f32 v247, v92, v93
	v_cvt_pk_bf16_f32 v248, v86, v87
	v_cvt_pk_bf16_f32 v249, v88, v89
	s_mov_b32 exec_lo, 0x80008000
	s_mov_b32 exec_hi, 0x80008000
	s_add_u32 s28, s27, 0x5800
	s_mov_b32 s29, 0
	v_lshl_add_u64 v[146:147], v[228:229], 0, s[28:29]
	global_store_dwordx4 v[146:147], v[242:245], off
	s_add_u32 s28, s28, 0x1600
	v_lshl_add_u64 v[146:147], v[228:229], 0, s[28:29]
	global_store_dwordx4 v[146:147], v[246:249], off
	v_cvt_pk_bf16_f32 v242, v82, v83
	v_cvt_pk_bf16_f32 v243, v84, v85
	v_cvt_pk_bf16_f32 v244, v78, v79
	v_cvt_pk_bf16_f32 v245, v80, v81
	v_cvt_pk_bf16_f32 v246, v74, v75
	v_cvt_pk_bf16_f32 v247, v76, v77
	v_cvt_pk_bf16_f32 v248, v70, v71
	v_cvt_pk_bf16_f32 v249, v72, v73
	s_add_u32 s28, s27, 0x8400
	s_mov_b32 s29, 0
	v_lshl_add_u64 v[146:147], v[228:229], 0, s[28:29]
	global_store_dwordx4 v[146:147], v[242:245], off
	s_add_u32 s28, s28, 0x1600
	v_lshl_add_u64 v[146:147], v[228:229], 0, s[28:29]
	global_store_dwordx4 v[146:147], v[246:249], off
	s_mov_b64 exec, -1
	v_cvt_pk_bf16_f32 v242, v66, v67
	v_cvt_pk_bf16_f32 v243, v68, v69
	v_cvt_pk_bf16_f32 v244, v62, v63
	v_cvt_pk_bf16_f32 v245, v64, v65
	v_cvt_pk_bf16_f32 v246, v58, v59
	v_cvt_pk_bf16_f32 v247, v60, v61
	v_cvt_pk_bf16_f32 v248, v54, v55
	v_cvt_pk_bf16_f32 v249, v56, v57
	s_mov_b32 exec_lo, 0x00010001
	s_mov_b32 exec_hi, 0x00010001
	s_add_u32 s28, s27, 0x16000
	s_mov_b32 s29, 0
	v_lshl_add_u64 v[146:147], v[228:229], 0, s[28:29]
	global_store_dwordx4 v[146:147], v[242:245], off
	s_add_u32 s28, s28, 0x1600
	v_lshl_add_u64 v[146:147], v[228:229], 0, s[28:29]
	global_store_dwordx4 v[146:147], v[246:249], off
	v_cvt_pk_bf16_f32 v242, v50, v51
	v_cvt_pk_bf16_f32 v243, v52, v53
	v_cvt_pk_bf16_f32 v244, v46, v47
	v_cvt_pk_bf16_f32 v245, v48, v49
	v_cvt_pk_bf16_f32 v246, v42, v43
	v_cvt_pk_bf16_f32 v247, v44, v45
	v_cvt_pk_bf16_f32 v248, v38, v39
	v_cvt_pk_bf16_f32 v249, v40, v41
	s_add_u32 s28, s27, 0x18c00
	s_mov_b32 s29, 0
	v_lshl_add_u64 v[146:147], v[228:229], 0, s[28:29]
	global_store_dwordx4 v[146:147], v[242:245], off
	s_add_u32 s28, s28, 0x1600
	v_lshl_add_u64 v[146:147], v[228:229], 0, s[28:29]
	global_store_dwordx4 v[146:147], v[246:249], off
	s_mov_b64 exec, -1
	v_cvt_pk_bf16_f32 v242, v34, v35
	v_cvt_pk_bf16_f32 v243, v36, v37
	v_cvt_pk_bf16_f32 v244, v30, v31
	v_cvt_pk_bf16_f32 v245, v32, v33
	v_cvt_pk_bf16_f32 v246, v26, v27
	v_cvt_pk_bf16_f32 v247, v28, v29
	v_cvt_pk_bf16_f32 v248, v22, v23
	v_cvt_pk_bf16_f32 v249, v24, v25
	s_mov_b32 exec_lo, 0x80008000
	s_mov_b32 exec_hi, 0x80008000
	s_add_u32 s28, s27, 0x1b800
	s_mov_b32 s29, 0
	v_lshl_add_u64 v[146:147], v[228:229], 0, s[28:29]
	global_store_dwordx4 v[146:147], v[242:245], off
	s_add_u32 s28, s28, 0x1600
	v_lshl_add_u64 v[146:147], v[228:229], 0, s[28:29]
	global_store_dwordx4 v[146:147], v[246:249], off
	v_cvt_pk_bf16_f32 v242, v18, v19
	v_cvt_pk_bf16_f32 v243, v20, v21
	v_cvt_pk_bf16_f32 v244, v14, v15
	v_cvt_pk_bf16_f32 v245, v16, v17
	v_cvt_pk_bf16_f32 v246, v10, v11
	v_cvt_pk_bf16_f32 v247, v12, v13
	v_cvt_pk_bf16_f32 v248, v6, v7
	v_cvt_pk_bf16_f32 v249, v8, v9
	s_add_u32 s28, s27, 0x1e400
	s_mov_b32 s29, 0
	v_lshl_add_u64 v[146:147], v[228:229], 0, s[28:29]
	global_store_dwordx4 v[146:147], v[242:245], off
	s_add_u32 s28, s28, 0x1600
	v_lshl_add_u64 v[146:147], v[228:229], 0, s[28:29]
	global_store_dwordx4 v[146:147], v[246:249], off
	s_mov_b64 exec, -1
	s_mov_b32 s30, 0xbfb8aa3b
	s_mov_b32 s31, 0xbfb8aa3b
	s_waitcnt vmcnt(16)
	v_pk_fma_f32 v[220:221], v[130:131], v[168:169], v[176:177]
	v_pk_fma_f32 v[222:223], v[114:115], v[168:169], v[176:177]
	v_fmac_f32_dpp v220, v82, v160 row_shr:1 row_mask:0xf bank_mask:0xf
	v_fmac_f32_dpp v220, v98, v152 row_shr:1 row_mask:0xf bank_mask:0xf
	v_fmac_f32_dpp v222, v82, v152 row_shr:1 row_mask:0xf bank_mask:0xf
	v_fmac_f32_dpp v221, v83, v161 row_shr:1 row_mask:0xf bank_mask:0xf
	v_fmac_f32_dpp v221, v99, v153 row_shr:1 row_mask:0xf bank_mask:0xf
	v_fmac_f32_dpp v223, v83, v153 row_shr:1 row_mask:0xf bank_mask:0xf
	v_pk_fma_f32 v[222:223], v[130:131], v[160:161], v[222:223]
	v_pk_fma_f32 v[82:83], v[82:83], v[168:169], v[176:177]
	v_pk_fma_f32 v[82:83], v[98:99], v[160:161], v[82:83]
	v_pk_fma_f32 v[82:83], v[114:115], v[152:153], v[82:83]
	v_pk_fma_f32 v[98:99], v[98:99], v[168:169], v[176:177]
	v_pk_fma_f32 v[98:99], v[114:115], v[160:161], v[98:99]
	v_pk_fma_f32 v[98:99], v[130:131], v[152:153], v[98:99]
	v_mov_b32_e32 v130, v220
	v_mov_b32_e32 v131, v221
	v_mov_b32_e32 v114, v222
	v_mov_b32_e32 v115, v223
	v_pk_fma_f32 v[220:221], v[132:133], v[170:171], v[178:179]
	v_pk_fma_f32 v[222:223], v[116:117], v[170:171], v[178:179]
	v_fmac_f32_dpp v220, v84, v162 row_shr:1 row_mask:0xf bank_mask:0xf
	v_fmac_f32_dpp v220, v100, v154 row_shr:1 row_mask:0xf bank_mask:0xf
	v_fmac_f32_dpp v222, v84, v154 row_shr:1 row_mask:0xf bank_mask:0xf
	v_fmac_f32_dpp v221, v85, v163 row_shr:1 row_mask:0xf bank_mask:0xf
	v_fmac_f32_dpp v221, v101, v155 row_shr:1 row_mask:0xf bank_mask:0xf
	v_fmac_f32_dpp v223, v85, v155 row_shr:1 row_mask:0xf bank_mask:0xf
	v_pk_fma_f32 v[222:223], v[132:133], v[162:163], v[222:223]
	v_pk_fma_f32 v[84:85], v[84:85], v[170:171], v[178:179]
	v_pk_fma_f32 v[84:85], v[100:101], v[162:163], v[84:85]
	v_pk_fma_f32 v[84:85], v[116:117], v[154:155], v[84:85]
	v_pk_fma_f32 v[100:101], v[100:101], v[170:171], v[178:179]
	v_pk_fma_f32 v[100:101], v[116:117], v[162:163], v[100:101]
	v_pk_fma_f32 v[100:101], v[132:133], v[154:155], v[100:101]
	v_mov_b32_e32 v132, v220
	v_mov_b32_e32 v133, v221
	v_mov_b32_e32 v116, v222
	v_mov_b32_e32 v117, v223
	v_pk_fma_f32 v[220:221], v[126:127], v[172:173], v[180:181]
	v_pk_fma_f32 v[222:223], v[110:111], v[172:173], v[180:181]
	v_fmac_f32_dpp v220, v78, v164 row_shr:1 row_mask:0xf bank_mask:0xf
	v_fmac_f32_dpp v220, v94, v156 row_shr:1 row_mask:0xf bank_mask:0xf
	v_fmac_f32_dpp v222, v78, v156 row_shr:1 row_mask:0xf bank_mask:0xf
	v_fmac_f32_dpp v221, v79, v165 row_shr:1 row_mask:0xf bank_mask:0xf
	v_fmac_f32_dpp v221, v95, v157 row_shr:1 row_mask:0xf bank_mask:0xf
	v_fmac_f32_dpp v223, v79, v157 row_shr:1 row_mask:0xf bank_mask:0xf
	v_pk_fma_f32 v[222:223], v[126:127], v[164:165], v[222:223]
	v_pk_fma_f32 v[78:79], v[78:79], v[172:173], v[180:181]
	v_pk_fma_f32 v[78:79], v[94:95], v[164:165], v[78:79]
	v_pk_fma_f32 v[78:79], v[110:111], v[156:157], v[78:79]
	v_pk_fma_f32 v[94:95], v[94:95], v[172:173], v[180:181]
	v_pk_fma_f32 v[94:95], v[110:111], v[164:165], v[94:95]
	v_pk_fma_f32 v[94:95], v[126:127], v[156:157], v[94:95]
	v_mov_b32_e32 v126, v220
	v_mov_b32_e32 v127, v221
	v_mov_b32_e32 v110, v222
	v_mov_b32_e32 v111, v223
	v_pk_fma_f32 v[220:221], v[128:129], v[174:175], v[182:183]
	v_pk_fma_f32 v[222:223], v[112:113], v[174:175], v[182:183]
	v_fmac_f32_dpp v220, v80, v166 row_shr:1 row_mask:0xf bank_mask:0xf
	v_fmac_f32_dpp v220, v96, v158 row_shr:1 row_mask:0xf bank_mask:0xf
	v_fmac_f32_dpp v222, v80, v158 row_shr:1 row_mask:0xf bank_mask:0xf
	v_fmac_f32_dpp v221, v81, v167 row_shr:1 row_mask:0xf bank_mask:0xf
	v_fmac_f32_dpp v221, v97, v159 row_shr:1 row_mask:0xf bank_mask:0xf
	v_fmac_f32_dpp v223, v81, v159 row_shr:1 row_mask:0xf bank_mask:0xf
	v_pk_fma_f32 v[222:223], v[128:129], v[166:167], v[222:223]
	v_pk_fma_f32 v[80:81], v[80:81], v[174:175], v[182:183]
	v_pk_fma_f32 v[80:81], v[96:97], v[166:167], v[80:81]
	v_pk_fma_f32 v[80:81], v[112:113], v[158:159], v[80:81]
	v_pk_fma_f32 v[96:97], v[96:97], v[174:175], v[182:183]
	v_pk_fma_f32 v[96:97], v[112:113], v[166:167], v[96:97]
	v_pk_fma_f32 v[96:97], v[128:129], v[158:159], v[96:97]
	v_mov_b32_e32 v128, v220
	v_mov_b32_e32 v129, v221
	v_mov_b32_e32 v112, v222
	v_mov_b32_e32 v113, v223
	v_pk_fma_f32 v[220:221], v[122:123], v[200:201], v[208:209]
	v_pk_fma_f32 v[222:223], v[106:107], v[200:201], v[208:209]
	v_fmac_f32_dpp v220, v74, v192 row_shr:1 row_mask:0xf bank_mask:0xf
	v_fmac_f32_dpp v220, v90, v184 row_shr:1 row_mask:0xf bank_mask:0xf
	v_fmac_f32_dpp v222, v74, v184 row_shr:1 row_mask:0xf bank_mask:0xf
	v_fmac_f32_dpp v221, v75, v193 row_shr:1 row_mask:0xf bank_mask:0xf
	v_fmac_f32_dpp v221, v91, v185 row_shr:1 row_mask:0xf bank_mask:0xf
	v_fmac_f32_dpp v223, v75, v185 row_shr:1 row_mask:0xf bank_mask:0xf
	v_pk_fma_f32 v[222:223], v[122:123], v[192:193], v[222:223]
	v_pk_fma_f32 v[74:75], v[74:75], v[200:201], v[208:209]
	v_pk_fma_f32 v[74:75], v[90:91], v[192:193], v[74:75]
	v_pk_fma_f32 v[74:75], v[106:107], v[184:185], v[74:75]
	v_pk_fma_f32 v[90:91], v[90:91], v[200:201], v[208:209]
	v_pk_fma_f32 v[90:91], v[106:107], v[192:193], v[90:91]
	v_pk_fma_f32 v[90:91], v[122:123], v[184:185], v[90:91]
	v_mov_b32_e32 v122, v220
	v_mov_b32_e32 v123, v221
	v_mov_b32_e32 v106, v222
	v_mov_b32_e32 v107, v223
	v_pk_fma_f32 v[220:221], v[124:125], v[202:203], v[210:211]
	v_pk_fma_f32 v[222:223], v[108:109], v[202:203], v[210:211]
	v_fmac_f32_dpp v220, v76, v194 row_shr:1 row_mask:0xf bank_mask:0xf
	v_fmac_f32_dpp v220, v92, v186 row_shr:1 row_mask:0xf bank_mask:0xf
	v_fmac_f32_dpp v222, v76, v186 row_shr:1 row_mask:0xf bank_mask:0xf
	v_fmac_f32_dpp v221, v77, v195 row_shr:1 row_mask:0xf bank_mask:0xf
	v_fmac_f32_dpp v221, v93, v187 row_shr:1 row_mask:0xf bank_mask:0xf
	v_fmac_f32_dpp v223, v77, v187 row_shr:1 row_mask:0xf bank_mask:0xf
	v_pk_fma_f32 v[222:223], v[124:125], v[194:195], v[222:223]
	v_pk_fma_f32 v[76:77], v[76:77], v[202:203], v[210:211]
	v_pk_fma_f32 v[76:77], v[92:93], v[194:195], v[76:77]
	v_pk_fma_f32 v[76:77], v[108:109], v[186:187], v[76:77]
	v_pk_fma_f32 v[92:93], v[92:93], v[202:203], v[210:211]
	v_pk_fma_f32 v[92:93], v[108:109], v[194:195], v[92:93]
	v_pk_fma_f32 v[92:93], v[124:125], v[186:187], v[92:93]
	v_mov_b32_e32 v124, v220
	v_mov_b32_e32 v125, v221
	v_mov_b32_e32 v108, v222
	v_mov_b32_e32 v109, v223
	v_pk_fma_f32 v[220:221], v[118:119], v[204:205], v[212:213]
	v_pk_fma_f32 v[222:223], v[102:103], v[204:205], v[212:213]
	v_fmac_f32_dpp v220, v70, v196 row_shr:1 row_mask:0xf bank_mask:0xf
	v_fmac_f32_dpp v220, v86, v188 row_shr:1 row_mask:0xf bank_mask:0xf
	v_fmac_f32_dpp v222, v70, v188 row_shr:1 row_mask:0xf bank_mask:0xf
	v_fmac_f32_dpp v221, v71, v197 row_shr:1 row_mask:0xf bank_mask:0xf
	v_fmac_f32_dpp v221, v87, v189 row_shr:1 row_mask:0xf bank_mask:0xf
	v_fmac_f32_dpp v223, v71, v189 row_shr:1 row_mask:0xf bank_mask:0xf
	v_pk_fma_f32 v[222:223], v[118:119], v[196:197], v[222:223]
	v_pk_fma_f32 v[70:71], v[70:71], v[204:205], v[212:213]
	v_pk_fma_f32 v[70:71], v[86:87], v[196:197], v[70:71]
	v_pk_fma_f32 v[70:71], v[102:103], v[188:189], v[70:71]
	v_pk_fma_f32 v[86:87], v[86:87], v[204:205], v[212:213]
	v_pk_fma_f32 v[86:87], v[102:103], v[196:197], v[86:87]
	v_pk_fma_f32 v[86:87], v[118:119], v[188:189], v[86:87]
	v_mov_b32_e32 v118, v220
	v_mov_b32_e32 v119, v221
	v_mov_b32_e32 v102, v222
	v_mov_b32_e32 v103, v223
	v_pk_fma_f32 v[220:221], v[120:121], v[206:207], v[214:215]
	v_pk_fma_f32 v[222:223], v[104:105], v[206:207], v[214:215]
	v_fmac_f32_dpp v220, v72, v198 row_shr:1 row_mask:0xf bank_mask:0xf
	v_fmac_f32_dpp v220, v88, v190 row_shr:1 row_mask:0xf bank_mask:0xf
	v_fmac_f32_dpp v222, v72, v190 row_shr:1 row_mask:0xf bank_mask:0xf
	v_fmac_f32_dpp v221, v73, v199 row_shr:1 row_mask:0xf bank_mask:0xf
	v_fmac_f32_dpp v221, v89, v191 row_shr:1 row_mask:0xf bank_mask:0xf
	v_fmac_f32_dpp v223, v73, v191 row_shr:1 row_mask:0xf bank_mask:0xf
	v_pk_fma_f32 v[222:223], v[120:121], v[198:199], v[222:223]
	v_pk_fma_f32 v[72:73], v[72:73], v[206:207], v[214:215]
	v_pk_fma_f32 v[72:73], v[88:89], v[198:199], v[72:73]
	v_pk_fma_f32 v[72:73], v[104:105], v[190:191], v[72:73]
	v_pk_fma_f32 v[88:89], v[88:89], v[206:207], v[214:215]
	v_pk_fma_f32 v[88:89], v[104:105], v[198:199], v[88:89]
	v_pk_fma_f32 v[88:89], v[120:121], v[190:191], v[88:89]
	v_mov_b32_e32 v120, v220
	v_mov_b32_e32 v121, v221
	v_mov_b32_e32 v104, v222
	v_mov_b32_e32 v105, v223
	v_pk_mul_f32 v[220:221], v[130:131], s[30:31]
	v_exp_f32_e32 v220, v220
	v_exp_f32_e32 v221, v221
	s_nop 0
	v_pk_add_f32 v[220:221], v[220:221], 1.0 op_sel_hi:[1,0]
	v_rcp_f32_e32 v220, v220
	v_rcp_f32_e32 v221, v221
	s_nop 0
	v_pk_mul_f32 v[220:221], v[220:221], v[130:131]
	v_pk_mul_f32 v[220:221], v[220:221], v[122:123]
	v_cvt_pk_bf16_f32 v224, v220, v221
	v_pk_mul_f32 v[220:221], v[132:133], s[30:31]
	v_exp_f32_e32 v220, v220
	v_exp_f32_e32 v221, v221
	s_nop 0
	v_pk_add_f32 v[220:221], v[220:221], 1.0 op_sel_hi:[1,0]
	v_rcp_f32_e32 v220, v220
	v_rcp_f32_e32 v221, v221
	s_nop 0
	v_pk_mul_f32 v[220:221], v[220:221], v[132:133]
	v_pk_mul_f32 v[220:221], v[220:221], v[124:125]
	v_cvt_pk_bf16_f32 v225, v220, v221
	v_pk_mul_f32 v[220:221], v[126:127], s[30:31]
	v_exp_f32_e32 v220, v220
	v_exp_f32_e32 v221, v221
	s_nop 0
	v_pk_add_f32 v[220:221], v[220:221], 1.0 op_sel_hi:[1,0]
	v_rcp_f32_e32 v220, v220
	v_rcp_f32_e32 v221, v221
	s_nop 0
	v_pk_mul_f32 v[220:221], v[220:221], v[126:127]
	v_pk_mul_f32 v[220:221], v[220:221], v[118:119]
	v_cvt_pk_bf16_f32 v226, v220, v221
	v_pk_mul_f32 v[220:221], v[128:129], s[30:31]
	v_exp_f32_e32 v220, v220
	v_exp_f32_e32 v221, v221
	s_nop 0
	v_pk_add_f32 v[220:221], v[220:221], 1.0 op_sel_hi:[1,0]
	v_rcp_f32_e32 v220, v220
	v_rcp_f32_e32 v221, v221
	s_nop 0
	v_pk_mul_f32 v[220:221], v[220:221], v[128:129]
	v_pk_mul_f32 v[220:221], v[220:221], v[120:121]
	v_cvt_pk_bf16_f32 v227, v220, v221
	ds_bpermute_b32 v242, v145, v224
	ds_bpermute_b32 v243, v145, v225
	ds_bpermute_b32 v244, v145, v226
	ds_bpermute_b32 v245, v145, v227
	s_mov_b32 s4, 0x0
	s_mov_b32 s5, 0
	v_lshl_add_u64 v[146:147], v[216:217], 0, s[4:5]
	v_pk_mul_f32 v[220:221], v[114:115], s[30:31]
	v_exp_f32_e32 v220, v220
	v_exp_f32_e32 v221, v221
	s_nop 0
	v_pk_add_f32 v[220:221], v[220:221], 1.0 op_sel_hi:[1,0]
	v_rcp_f32_e32 v220, v220
	v_rcp_f32_e32 v221, v221
	s_nop 0
	v_pk_mul_f32 v[220:221], v[220:221], v[114:115]
	v_pk_mul_f32 v[220:221], v[220:221], v[106:107]
	v_cvt_pk_bf16_f32 v224, v220, v221
	v_pk_mul_f32 v[220:221], v[116:117], s[30:31]
	v_exp_f32_e32 v220, v220
	v_exp_f32_e32 v221, v221
	s_nop 0
	v_pk_add_f32 v[220:221], v[220:221], 1.0 op_sel_hi:[1,0]
	v_rcp_f32_e32 v220, v220
	v_rcp_f32_e32 v221, v221
	s_nop 0
	v_pk_mul_f32 v[220:221], v[220:221], v[116:117]
	v_pk_mul_f32 v[220:221], v[220:221], v[108:109]
	v_cvt_pk_bf16_f32 v225, v220, v221
	v_pk_mul_f32 v[220:221], v[110:111], s[30:31]
	v_exp_f32_e32 v220, v220
	v_exp_f32_e32 v221, v221
	s_nop 0
	v_pk_add_f32 v[220:221], v[220:221], 1.0 op_sel_hi:[1,0]
	v_rcp_f32_e32 v220, v220
	v_rcp_f32_e32 v221, v221
	s_nop 0
	v_pk_mul_f32 v[220:221], v[220:221], v[110:111]
	v_pk_mul_f32 v[220:221], v[220:221], v[102:103]
	v_cvt_pk_bf16_f32 v226, v220, v221
	v_pk_mul_f32 v[220:221], v[112:113], s[30:31]
	v_exp_f32_e32 v220, v220
	v_exp_f32_e32 v221, v221
	s_nop 0
	v_pk_add_f32 v[220:221], v[220:221], 1.0 op_sel_hi:[1,0]
	v_rcp_f32_e32 v220, v220
	v_rcp_f32_e32 v221, v221
	s_nop 0
	v_pk_mul_f32 v[220:221], v[220:221], v[112:113]
	v_pk_mul_f32 v[220:221], v[220:221], v[104:105]
	v_cvt_pk_bf16_f32 v227, v220, v221
	ds_bpermute_b32 v246, v145, v224
	ds_bpermute_b32 v247, v145, v225
	ds_bpermute_b32 v248, v145, v226
	ds_bpermute_b32 v249, v145, v227
	s_mov_b32 s4, 0x1600
	s_mov_b32 s5, 0
	v_lshl_add_u64 v[228:229], v[216:217], 0, s[4:5]
	s_waitcnt lgkmcnt(4)
	global_store_dwordx4 v[146:147], v[242:245], off
	v_pk_mul_f32 v[220:221], v[98:99], s[30:31]
	v_exp_f32_e32 v220, v220
	v_exp_f32_e32 v221, v221
	s_nop 0
	v_pk_add_f32 v[220:221], v[220:221], 1.0 op_sel_hi:[1,0]
	v_rcp_f32_e32 v220, v220
	v_rcp_f32_e32 v221, v221
	s_nop 0
	v_pk_mul_f32 v[220:221], v[220:221], v[98:99]
	v_pk_mul_f32 v[220:221], v[220:221], v[90:91]
	v_cvt_pk_bf16_f32 v224, v220, v221
	v_pk_mul_f32 v[220:221], v[100:101], s[30:31]
	v_exp_f32_e32 v220, v220
	v_exp_f32_e32 v221, v221
	s_nop 0
	v_pk_add_f32 v[220:221], v[220:221], 1.0 op_sel_hi:[1,0]
	v_rcp_f32_e32 v220, v220
	v_rcp_f32_e32 v221, v221
	s_nop 0
	v_pk_mul_f32 v[220:221], v[220:221], v[100:101]
	v_pk_mul_f32 v[220:221], v[220:221], v[92:93]
	v_cvt_pk_bf16_f32 v225, v220, v221
	v_pk_mul_f32 v[220:221], v[94:95], s[30:31]
	v_exp_f32_e32 v220, v220
	v_exp_f32_e32 v221, v221
	s_nop 0
	v_pk_add_f32 v[220:221], v[220:221], 1.0 op_sel_hi:[1,0]
	v_rcp_f32_e32 v220, v220
	v_rcp_f32_e32 v221, v221
	s_nop 0
	v_pk_mul_f32 v[220:221], v[220:221], v[94:95]
	v_pk_mul_f32 v[220:221], v[220:221], v[86:87]
	v_cvt_pk_bf16_f32 v226, v220, v221
	v_pk_mul_f32 v[220:221], v[96:97], s[30:31]
	v_exp_f32_e32 v220, v220
	v_exp_f32_e32 v221, v221
	s_nop 0
	v_pk_add_f32 v[220:221], v[220:221], 1.0 op_sel_hi:[1,0]
	v_rcp_f32_e32 v220, v220
	v_rcp_f32_e32 v221, v221
	s_nop 0
	v_pk_mul_f32 v[220:221], v[220:221], v[96:97]
	v_pk_mul_f32 v[220:221], v[220:221], v[88:89]
	v_cvt_pk_bf16_f32 v227, v220, v221
	ds_bpermute_b32 v242, v145, v224
	ds_bpermute_b32 v243, v145, v225
	ds_bpermute_b32 v244, v145, v226
	ds_bpermute_b32 v245, v145, v227
	s_mov_b32 s4, 0x2c00
	s_mov_b32 s5, 0
	v_lshl_add_u64 v[146:147], v[216:217], 0, s[4:5]
	s_waitcnt lgkmcnt(4)
	global_store_dwordx4 v[228:229], v[246:249], off
	v_pk_mul_f32 v[220:221], v[82:83], s[30:31]
	v_exp_f32_e32 v220, v220
	v_exp_f32_e32 v221, v221
	s_nop 0
	v_pk_add_f32 v[220:221], v[220:221], 1.0 op_sel_hi:[1,0]
	v_rcp_f32_e32 v220, v220
	v_rcp_f32_e32 v221, v221
	s_nop 0
	v_pk_mul_f32 v[220:221], v[220:221], v[82:83]
	v_pk_mul_f32 v[220:221], v[220:221], v[74:75]
	v_cvt_pk_bf16_f32 v224, v220, v221
	v_pk_mul_f32 v[220:221], v[84:85], s[30:31]
	v_exp_f32_e32 v220, v220
	v_exp_f32_e32 v221, v221
	s_nop 0
	v_pk_add_f32 v[220:221], v[220:221], 1.0 op_sel_hi:[1,0]
	v_rcp_f32_e32 v220, v220
	v_rcp_f32_e32 v221, v221
	s_nop 0
	v_pk_mul_f32 v[220:221], v[220:221], v[84:85]
	v_pk_mul_f32 v[220:221], v[220:221], v[76:77]
	v_cvt_pk_bf16_f32 v225, v220, v221
	v_pk_mul_f32 v[220:221], v[78:79], s[30:31]
	v_exp_f32_e32 v220, v220
	v_exp_f32_e32 v221, v221
	s_nop 0
	v_pk_add_f32 v[220:221], v[220:221], 1.0 op_sel_hi:[1,0]
	v_rcp_f32_e32 v220, v220
	v_rcp_f32_e32 v221, v221
	s_nop 0
	v_pk_mul_f32 v[220:221], v[220:221], v[78:79]
	v_pk_mul_f32 v[220:221], v[220:221], v[70:71]
	v_cvt_pk_bf16_f32 v226, v220, v221
	v_pk_mul_f32 v[220:221], v[80:81], s[30:31]
	v_exp_f32_e32 v220, v220
	v_exp_f32_e32 v221, v221
	s_nop 0
	v_pk_add_f32 v[220:221], v[220:221], 1.0 op_sel_hi:[1,0]
	v_rcp_f32_e32 v220, v220
	v_rcp_f32_e32 v221, v221
	s_nop 0
	v_pk_mul_f32 v[220:221], v[220:221], v[80:81]
	v_pk_mul_f32 v[220:221], v[220:221], v[72:73]
	v_cvt_pk_bf16_f32 v227, v220, v221
	ds_bpermute_b32 v246, v145, v224
	ds_bpermute_b32 v247, v145, v225
	ds_bpermute_b32 v248, v145, v226
	ds_bpermute_b32 v249, v145, v227
	s_mov_b32 s4, 0x4200
	s_mov_b32 s5, 0
	v_lshl_add_u64 v[228:229], v[216:217], 0, s[4:5]
	s_waitcnt lgkmcnt(4)
	global_store_dwordx4 v[146:147], v[242:245], off
	v_pk_fma_f32 v[220:221], v[66:67], v[168:169], v[176:177]
	v_pk_fma_f32 v[222:223], v[50:51], v[168:169], v[176:177]
	v_fmac_f32_dpp v220, v18, v160 row_shr:1 row_mask:0xf bank_mask:0xf
	v_fmac_f32_dpp v220, v34, v152 row_shr:1 row_mask:0xf bank_mask:0xf
	v_fmac_f32_dpp v222, v18, v152 row_shr:1 row_mask:0xf bank_mask:0xf
	v_fmac_f32_dpp v221, v19, v161 row_shr:1 row_mask:0xf bank_mask:0xf
	v_fmac_f32_dpp v221, v35, v153 row_shr:1 row_mask:0xf bank_mask:0xf
	v_fmac_f32_dpp v223, v19, v153 row_shr:1 row_mask:0xf bank_mask:0xf
	v_pk_fma_f32 v[222:223], v[66:67], v[160:161], v[222:223]
	v_pk_fma_f32 v[18:19], v[18:19], v[168:169], v[176:177]
	v_pk_fma_f32 v[18:19], v[34:35], v[160:161], v[18:19]
	v_pk_fma_f32 v[18:19], v[50:51], v[152:153], v[18:19]
	v_pk_fma_f32 v[34:35], v[34:35], v[168:169], v[176:177]
	v_pk_fma_f32 v[34:35], v[50:51], v[160:161], v[34:35]
	v_pk_fma_f32 v[34:35], v[66:67], v[152:153], v[34:35]
	v_mov_b32_e32 v66, v220
	v_mov_b32_e32 v67, v221
	v_mov_b32_e32 v50, v222
	v_mov_b32_e32 v51, v223
	v_pk_fma_f32 v[220:221], v[68:69], v[170:171], v[178:179]
	v_pk_fma_f32 v[222:223], v[52:53], v[170:171], v[178:179]
	v_fmac_f32_dpp v220, v20, v162 row_shr:1 row_mask:0xf bank_mask:0xf
	v_fmac_f32_dpp v220, v36, v154 row_shr:1 row_mask:0xf bank_mask:0xf
	v_fmac_f32_dpp v222, v20, v154 row_shr:1 row_mask:0xf bank_mask:0xf
	v_fmac_f32_dpp v221, v21, v163 row_shr:1 row_mask:0xf bank_mask:0xf
	v_fmac_f32_dpp v221, v37, v155 row_shr:1 row_mask:0xf bank_mask:0xf
	v_fmac_f32_dpp v223, v21, v155 row_shr:1 row_mask:0xf bank_mask:0xf
	v_pk_fma_f32 v[222:223], v[68:69], v[162:163], v[222:223]
	v_pk_fma_f32 v[20:21], v[20:21], v[170:171], v[178:179]
	v_pk_fma_f32 v[20:21], v[36:37], v[162:163], v[20:21]
	v_pk_fma_f32 v[20:21], v[52:53], v[154:155], v[20:21]
	v_pk_fma_f32 v[36:37], v[36:37], v[170:171], v[178:179]
	v_pk_fma_f32 v[36:37], v[52:53], v[162:163], v[36:37]
	v_pk_fma_f32 v[36:37], v[68:69], v[154:155], v[36:37]
	v_mov_b32_e32 v68, v220
	v_mov_b32_e32 v69, v221
	v_mov_b32_e32 v52, v222
	v_mov_b32_e32 v53, v223
	v_pk_fma_f32 v[220:221], v[62:63], v[172:173], v[180:181]
	v_pk_fma_f32 v[222:223], v[46:47], v[172:173], v[180:181]
	v_fmac_f32_dpp v220, v14, v164 row_shr:1 row_mask:0xf bank_mask:0xf
	v_fmac_f32_dpp v220, v30, v156 row_shr:1 row_mask:0xf bank_mask:0xf
	v_fmac_f32_dpp v222, v14, v156 row_shr:1 row_mask:0xf bank_mask:0xf
	v_fmac_f32_dpp v221, v15, v165 row_shr:1 row_mask:0xf bank_mask:0xf
	v_fmac_f32_dpp v221, v31, v157 row_shr:1 row_mask:0xf bank_mask:0xf
	v_fmac_f32_dpp v223, v15, v157 row_shr:1 row_mask:0xf bank_mask:0xf
	v_pk_fma_f32 v[222:223], v[62:63], v[164:165], v[222:223]
	v_pk_fma_f32 v[14:15], v[14:15], v[172:173], v[180:181]
	v_pk_fma_f32 v[14:15], v[30:31], v[164:165], v[14:15]
	v_pk_fma_f32 v[14:15], v[46:47], v[156:157], v[14:15]
	v_pk_fma_f32 v[30:31], v[30:31], v[172:173], v[180:181]
	v_pk_fma_f32 v[30:31], v[46:47], v[164:165], v[30:31]
	v_pk_fma_f32 v[30:31], v[62:63], v[156:157], v[30:31]
	v_mov_b32_e32 v62, v220
	v_mov_b32_e32 v63, v221
	v_mov_b32_e32 v46, v222
	v_mov_b32_e32 v47, v223
	v_pk_fma_f32 v[220:221], v[64:65], v[174:175], v[182:183]
	v_pk_fma_f32 v[222:223], v[48:49], v[174:175], v[182:183]
	v_fmac_f32_dpp v220, v16, v166 row_shr:1 row_mask:0xf bank_mask:0xf
	v_fmac_f32_dpp v220, v32, v158 row_shr:1 row_mask:0xf bank_mask:0xf
	v_fmac_f32_dpp v222, v16, v158 row_shr:1 row_mask:0xf bank_mask:0xf
	v_fmac_f32_dpp v221, v17, v167 row_shr:1 row_mask:0xf bank_mask:0xf
	v_fmac_f32_dpp v221, v33, v159 row_shr:1 row_mask:0xf bank_mask:0xf
	v_fmac_f32_dpp v223, v17, v159 row_shr:1 row_mask:0xf bank_mask:0xf
	v_pk_fma_f32 v[222:223], v[64:65], v[166:167], v[222:223]
	v_pk_fma_f32 v[16:17], v[16:17], v[174:175], v[182:183]
	v_pk_fma_f32 v[16:17], v[32:33], v[166:167], v[16:17]
	v_pk_fma_f32 v[16:17], v[48:49], v[158:159], v[16:17]
	v_pk_fma_f32 v[32:33], v[32:33], v[174:175], v[182:183]
	v_pk_fma_f32 v[32:33], v[48:49], v[166:167], v[32:33]
	v_pk_fma_f32 v[32:33], v[64:65], v[158:159], v[32:33]
	v_mov_b32_e32 v64, v220
	v_mov_b32_e32 v65, v221
	v_mov_b32_e32 v48, v222
	v_mov_b32_e32 v49, v223
	v_pk_fma_f32 v[220:221], v[58:59], v[200:201], v[208:209]
	v_pk_fma_f32 v[222:223], v[42:43], v[200:201], v[208:209]
	v_fmac_f32_dpp v220, v10, v192 row_shr:1 row_mask:0xf bank_mask:0xf
	v_fmac_f32_dpp v220, v26, v184 row_shr:1 row_mask:0xf bank_mask:0xf
	v_fmac_f32_dpp v222, v10, v184 row_shr:1 row_mask:0xf bank_mask:0xf
	v_fmac_f32_dpp v221, v11, v193 row_shr:1 row_mask:0xf bank_mask:0xf
	v_fmac_f32_dpp v221, v27, v185 row_shr:1 row_mask:0xf bank_mask:0xf
	v_fmac_f32_dpp v223, v11, v185 row_shr:1 row_mask:0xf bank_mask:0xf
	v_pk_fma_f32 v[222:223], v[58:59], v[192:193], v[222:223]
	v_pk_fma_f32 v[10:11], v[10:11], v[200:201], v[208:209]
	v_pk_fma_f32 v[10:11], v[26:27], v[192:193], v[10:11]
	v_pk_fma_f32 v[10:11], v[42:43], v[184:185], v[10:11]
	v_pk_fma_f32 v[26:27], v[26:27], v[200:201], v[208:209]
	v_pk_fma_f32 v[26:27], v[42:43], v[192:193], v[26:27]
	v_pk_fma_f32 v[26:27], v[58:59], v[184:185], v[26:27]
	v_mov_b32_e32 v58, v220
	v_mov_b32_e32 v59, v221
	v_mov_b32_e32 v42, v222
	v_mov_b32_e32 v43, v223
	v_pk_fma_f32 v[220:221], v[60:61], v[202:203], v[210:211]
	v_pk_fma_f32 v[222:223], v[44:45], v[202:203], v[210:211]
	v_fmac_f32_dpp v220, v12, v194 row_shr:1 row_mask:0xf bank_mask:0xf
	v_fmac_f32_dpp v220, v28, v186 row_shr:1 row_mask:0xf bank_mask:0xf
	v_fmac_f32_dpp v222, v12, v186 row_shr:1 row_mask:0xf bank_mask:0xf
	v_fmac_f32_dpp v221, v13, v195 row_shr:1 row_mask:0xf bank_mask:0xf
	v_fmac_f32_dpp v221, v29, v187 row_shr:1 row_mask:0xf bank_mask:0xf
	v_fmac_f32_dpp v223, v13, v187 row_shr:1 row_mask:0xf bank_mask:0xf
	v_pk_fma_f32 v[222:223], v[60:61], v[194:195], v[222:223]
	v_pk_fma_f32 v[12:13], v[12:13], v[202:203], v[210:211]
	v_pk_fma_f32 v[12:13], v[28:29], v[194:195], v[12:13]
	v_pk_fma_f32 v[12:13], v[44:45], v[186:187], v[12:13]
	v_pk_fma_f32 v[28:29], v[28:29], v[202:203], v[210:211]
	v_pk_fma_f32 v[28:29], v[44:45], v[194:195], v[28:29]
	v_pk_fma_f32 v[28:29], v[60:61], v[186:187], v[28:29]
	v_mov_b32_e32 v60, v220
	v_mov_b32_e32 v61, v221
	v_mov_b32_e32 v44, v222
	v_mov_b32_e32 v45, v223
	v_pk_fma_f32 v[220:221], v[54:55], v[204:205], v[212:213]
	v_pk_fma_f32 v[222:223], v[38:39], v[204:205], v[212:213]
	v_fmac_f32_dpp v220, v6, v196 row_shr:1 row_mask:0xf bank_mask:0xf
	v_fmac_f32_dpp v220, v22, v188 row_shr:1 row_mask:0xf bank_mask:0xf
	v_fmac_f32_dpp v222, v6, v188 row_shr:1 row_mask:0xf bank_mask:0xf
	v_fmac_f32_dpp v221, v7, v197 row_shr:1 row_mask:0xf bank_mask:0xf
	v_fmac_f32_dpp v221, v23, v189 row_shr:1 row_mask:0xf bank_mask:0xf
	v_fmac_f32_dpp v223, v7, v189 row_shr:1 row_mask:0xf bank_mask:0xf
	v_pk_fma_f32 v[222:223], v[54:55], v[196:197], v[222:223]
	v_pk_fma_f32 v[6:7], v[6:7], v[204:205], v[212:213]
	v_pk_fma_f32 v[6:7], v[22:23], v[196:197], v[6:7]
	v_pk_fma_f32 v[6:7], v[38:39], v[188:189], v[6:7]
	v_pk_fma_f32 v[22:23], v[22:23], v[204:205], v[212:213]
	v_pk_fma_f32 v[22:23], v[38:39], v[196:197], v[22:23]
	v_pk_fma_f32 v[22:23], v[54:55], v[188:189], v[22:23]
	v_mov_b32_e32 v54, v220
	v_mov_b32_e32 v55, v221
	v_mov_b32_e32 v38, v222
	v_mov_b32_e32 v39, v223
	v_pk_fma_f32 v[220:221], v[56:57], v[206:207], v[214:215]
	v_pk_fma_f32 v[222:223], v[40:41], v[206:207], v[214:215]
	v_fmac_f32_dpp v220, v8, v198 row_shr:1 row_mask:0xf bank_mask:0xf
	v_fmac_f32_dpp v220, v24, v190 row_shr:1 row_mask:0xf bank_mask:0xf
	v_fmac_f32_dpp v222, v8, v190 row_shr:1 row_mask:0xf bank_mask:0xf
	v_fmac_f32_dpp v221, v9, v199 row_shr:1 row_mask:0xf bank_mask:0xf
	v_fmac_f32_dpp v221, v25, v191 row_shr:1 row_mask:0xf bank_mask:0xf
	v_fmac_f32_dpp v223, v9, v191 row_shr:1 row_mask:0xf bank_mask:0xf
	v_pk_fma_f32 v[222:223], v[56:57], v[198:199], v[222:223]
	v_pk_fma_f32 v[8:9], v[8:9], v[206:207], v[214:215]
	v_pk_fma_f32 v[8:9], v[24:25], v[198:199], v[8:9]
	v_pk_fma_f32 v[8:9], v[40:41], v[190:191], v[8:9]
	v_pk_fma_f32 v[24:25], v[24:25], v[206:207], v[214:215]
	v_pk_fma_f32 v[24:25], v[40:41], v[198:199], v[24:25]
	v_pk_fma_f32 v[24:25], v[56:57], v[190:191], v[24:25]
	v_mov_b32_e32 v56, v220
	v_mov_b32_e32 v57, v221
	v_mov_b32_e32 v40, v222
	v_mov_b32_e32 v41, v223
	v_pk_mul_f32 v[220:221], v[66:67], s[30:31]
	v_exp_f32_e32 v220, v220
	v_exp_f32_e32 v221, v221
	s_nop 0
	v_pk_add_f32 v[220:221], v[220:221], 1.0 op_sel_hi:[1,0]
	v_rcp_f32_e32 v220, v220
	v_rcp_f32_e32 v221, v221
	s_nop 0
	v_pk_mul_f32 v[220:221], v[220:221], v[66:67]
	v_pk_mul_f32 v[220:221], v[220:221], v[58:59]
	v_cvt_pk_bf16_f32 v224, v220, v221
	v_pk_mul_f32 v[220:221], v[68:69], s[30:31]
	v_exp_f32_e32 v220, v220
	v_exp_f32_e32 v221, v221
	s_nop 0
	v_pk_add_f32 v[220:221], v[220:221], 1.0 op_sel_hi:[1,0]
	v_rcp_f32_e32 v220, v220
	v_rcp_f32_e32 v221, v221
	s_nop 0
	v_pk_mul_f32 v[220:221], v[220:221], v[68:69]
	v_pk_mul_f32 v[220:221], v[220:221], v[60:61]
	v_cvt_pk_bf16_f32 v225, v220, v221
	v_pk_mul_f32 v[220:221], v[62:63], s[30:31]
	v_exp_f32_e32 v220, v220
	v_exp_f32_e32 v221, v221
	s_nop 0
	v_pk_add_f32 v[220:221], v[220:221], 1.0 op_sel_hi:[1,0]
	v_rcp_f32_e32 v220, v220
	v_rcp_f32_e32 v221, v221
	s_nop 0
	v_pk_mul_f32 v[220:221], v[220:221], v[62:63]
	v_pk_mul_f32 v[220:221], v[220:221], v[54:55]
	v_cvt_pk_bf16_f32 v226, v220, v221
	v_pk_mul_f32 v[220:221], v[64:65], s[30:31]
	v_exp_f32_e32 v220, v220
	v_exp_f32_e32 v221, v221
	s_nop 0
	v_pk_add_f32 v[220:221], v[220:221], 1.0 op_sel_hi:[1,0]
	v_rcp_f32_e32 v220, v220
	v_rcp_f32_e32 v221, v221
	s_nop 0
	v_pk_mul_f32 v[220:221], v[220:221], v[64:65]
	v_pk_mul_f32 v[220:221], v[220:221], v[56:57]
	v_cvt_pk_bf16_f32 v227, v220, v221
	ds_bpermute_b32 v242, v145, v224
	ds_bpermute_b32 v243, v145, v225
	ds_bpermute_b32 v244, v145, v226
	ds_bpermute_b32 v245, v145, v227
	s_mov_b32 s4, 0xb0000
	s_mov_b32 s5, 0
	v_lshl_add_u64 v[146:147], v[216:217], 0, s[4:5]
	s_waitcnt lgkmcnt(4)
	global_store_dwordx4 v[228:229], v[246:249], off
	v_pk_mul_f32 v[220:221], v[50:51], s[30:31]
	v_exp_f32_e32 v220, v220
	v_exp_f32_e32 v221, v221
	s_nop 0
	v_pk_add_f32 v[220:221], v[220:221], 1.0 op_sel_hi:[1,0]
	v_rcp_f32_e32 v220, v220
	v_rcp_f32_e32 v221, v221
	s_nop 0
	v_pk_mul_f32 v[220:221], v[220:221], v[50:51]
	v_pk_mul_f32 v[220:221], v[220:221], v[42:43]
	v_cvt_pk_bf16_f32 v224, v220, v221
	v_pk_mul_f32 v[220:221], v[52:53], s[30:31]
	v_exp_f32_e32 v220, v220
	v_exp_f32_e32 v221, v221
	s_nop 0
	v_pk_add_f32 v[220:221], v[220:221], 1.0 op_sel_hi:[1,0]
	v_rcp_f32_e32 v220, v220
	v_rcp_f32_e32 v221, v221
	s_nop 0
	v_pk_mul_f32 v[220:221], v[220:221], v[52:53]
	v_pk_mul_f32 v[220:221], v[220:221], v[44:45]
	v_cvt_pk_bf16_f32 v225, v220, v221
	v_pk_mul_f32 v[220:221], v[46:47], s[30:31]
	v_exp_f32_e32 v220, v220
	v_exp_f32_e32 v221, v221
	s_nop 0
	v_pk_add_f32 v[220:221], v[220:221], 1.0 op_sel_hi:[1,0]
	v_rcp_f32_e32 v220, v220
	v_rcp_f32_e32 v221, v221
	s_nop 0
	v_pk_mul_f32 v[220:221], v[220:221], v[46:47]
	v_pk_mul_f32 v[220:221], v[220:221], v[38:39]
	v_cvt_pk_bf16_f32 v226, v220, v221
	v_pk_mul_f32 v[220:221], v[48:49], s[30:31]
	v_exp_f32_e32 v220, v220
	v_exp_f32_e32 v221, v221
	s_nop 0
	v_pk_add_f32 v[220:221], v[220:221], 1.0 op_sel_hi:[1,0]
	v_rcp_f32_e32 v220, v220
	v_rcp_f32_e32 v221, v221
	s_nop 0
	v_pk_mul_f32 v[220:221], v[220:221], v[48:49]
	v_pk_mul_f32 v[220:221], v[220:221], v[40:41]
	v_cvt_pk_bf16_f32 v227, v220, v221
	ds_bpermute_b32 v246, v145, v224
	ds_bpermute_b32 v247, v145, v225
	ds_bpermute_b32 v248, v145, v226
	ds_bpermute_b32 v249, v145, v227
	s_mov_b32 s4, 0xb1600
	s_mov_b32 s5, 0
	v_lshl_add_u64 v[228:229], v[216:217], 0, s[4:5]
	s_waitcnt lgkmcnt(4)
	global_store_dwordx4 v[146:147], v[242:245], off
	v_pk_mul_f32 v[220:221], v[34:35], s[30:31]
	v_exp_f32_e32 v220, v220
	v_exp_f32_e32 v221, v221
	s_nop 0
	v_pk_add_f32 v[220:221], v[220:221], 1.0 op_sel_hi:[1,0]
	v_rcp_f32_e32 v220, v220
	v_rcp_f32_e32 v221, v221
	s_nop 0
	v_pk_mul_f32 v[220:221], v[220:221], v[34:35]
	v_pk_mul_f32 v[220:221], v[220:221], v[26:27]
	v_cvt_pk_bf16_f32 v224, v220, v221
	v_pk_mul_f32 v[220:221], v[36:37], s[30:31]
	v_exp_f32_e32 v220, v220
	v_exp_f32_e32 v221, v221
	s_nop 0
	v_pk_add_f32 v[220:221], v[220:221], 1.0 op_sel_hi:[1,0]
	v_rcp_f32_e32 v220, v220
	v_rcp_f32_e32 v221, v221
	s_nop 0
	v_pk_mul_f32 v[220:221], v[220:221], v[36:37]
	v_pk_mul_f32 v[220:221], v[220:221], v[28:29]
	v_cvt_pk_bf16_f32 v225, v220, v221
	v_pk_mul_f32 v[220:221], v[30:31], s[30:31]
	v_exp_f32_e32 v220, v220
	v_exp_f32_e32 v221, v221
	s_nop 0
	v_pk_add_f32 v[220:221], v[220:221], 1.0 op_sel_hi:[1,0]
	v_rcp_f32_e32 v220, v220
	v_rcp_f32_e32 v221, v221
	s_nop 0
	v_pk_mul_f32 v[220:221], v[220:221], v[30:31]
	v_pk_mul_f32 v[220:221], v[220:221], v[22:23]
	v_cvt_pk_bf16_f32 v226, v220, v221
	v_pk_mul_f32 v[220:221], v[32:33], s[30:31]
	v_exp_f32_e32 v220, v220
	v_exp_f32_e32 v221, v221
	s_nop 0
	v_pk_add_f32 v[220:221], v[220:221], 1.0 op_sel_hi:[1,0]
	v_rcp_f32_e32 v220, v220
	v_rcp_f32_e32 v221, v221
	s_nop 0
	v_pk_mul_f32 v[220:221], v[220:221], v[32:33]
	v_pk_mul_f32 v[220:221], v[220:221], v[24:25]
	v_cvt_pk_bf16_f32 v227, v220, v221
	ds_bpermute_b32 v242, v145, v224
	ds_bpermute_b32 v243, v145, v225
	ds_bpermute_b32 v244, v145, v226
	ds_bpermute_b32 v245, v145, v227
	s_mov_b32 s4, 0xb2c00
	s_mov_b32 s5, 0
	v_lshl_add_u64 v[146:147], v[216:217], 0, s[4:5]
	s_waitcnt lgkmcnt(4)
	global_store_dwordx4 v[228:229], v[246:249], off
	v_pk_mul_f32 v[220:221], v[18:19], s[30:31]
	v_exp_f32_e32 v220, v220
	v_exp_f32_e32 v221, v221
	s_nop 0
	v_pk_add_f32 v[220:221], v[220:221], 1.0 op_sel_hi:[1,0]
	v_rcp_f32_e32 v220, v220
	v_rcp_f32_e32 v221, v221
	s_nop 0
	v_pk_mul_f32 v[220:221], v[220:221], v[18:19]
	v_pk_mul_f32 v[220:221], v[220:221], v[10:11]
	v_cvt_pk_bf16_f32 v224, v220, v221
	v_pk_mul_f32 v[220:221], v[20:21], s[30:31]
	v_exp_f32_e32 v220, v220
	v_exp_f32_e32 v221, v221
	s_nop 0
	v_pk_add_f32 v[220:221], v[220:221], 1.0 op_sel_hi:[1,0]
	v_rcp_f32_e32 v220, v220
	v_rcp_f32_e32 v221, v221
	s_nop 0
	v_pk_mul_f32 v[220:221], v[220:221], v[20:21]
	v_pk_mul_f32 v[220:221], v[220:221], v[12:13]
	v_cvt_pk_bf16_f32 v225, v220, v221
	v_pk_mul_f32 v[220:221], v[14:15], s[30:31]
	v_exp_f32_e32 v220, v220
	v_exp_f32_e32 v221, v221
	s_nop 0
	v_pk_add_f32 v[220:221], v[220:221], 1.0 op_sel_hi:[1,0]
	v_rcp_f32_e32 v220, v220
	v_rcp_f32_e32 v221, v221
	s_nop 0
	v_pk_mul_f32 v[220:221], v[220:221], v[14:15]
	v_pk_mul_f32 v[220:221], v[220:221], v[6:7]
	v_cvt_pk_bf16_f32 v226, v220, v221
	v_pk_mul_f32 v[220:221], v[16:17], s[30:31]
	v_exp_f32_e32 v220, v220
	v_exp_f32_e32 v221, v221
	s_nop 0
	v_pk_add_f32 v[220:221], v[220:221], 1.0 op_sel_hi:[1,0]
	v_rcp_f32_e32 v220, v220
	v_rcp_f32_e32 v221, v221
	s_nop 0
	v_pk_mul_f32 v[220:221], v[220:221], v[16:17]
	v_pk_mul_f32 v[220:221], v[220:221], v[8:9]
	v_cvt_pk_bf16_f32 v227, v220, v221
	ds_bpermute_b32 v246, v145, v224
	ds_bpermute_b32 v247, v145, v225
	ds_bpermute_b32 v248, v145, v226
	ds_bpermute_b32 v249, v145, v227
	s_mov_b32 s4, 0xb4200
	s_mov_b32 s5, 0
	v_lshl_add_u64 v[228:229], v[216:217], 0, s[4:5]
	s_waitcnt lgkmcnt(4)
	global_store_dwordx4 v[146:147], v[242:245], off
	s_waitcnt lgkmcnt(0)
	global_store_dwordx4 v[228:229], v[246:249], off
	s_branch .Lup_epi_done

.LBB0_308:
	v_readlane_b32 s30, v253, 41
	v_readlane_b32 s31, v253, 29
	s_lshl_b32 s38, s30, 1
	s_cmp_eq_u32 s31, 8
	s_cselect_b32 s31, 1, 0
	s_add_i32 s38, s38, s31
	s_ashr_i32 s25, s76, 5
	s_mul_i32 s25, s25, 0x18000
	s_add_u32 s36, s18, s25
	s_addc_u32 s37, s19, 0
	v_lshlrev_b64 v[226:227], 2, v[194:195]
	v_ashrrev_i32_e32 v193, 31, v192
	v_lshlrev_b64 v[228:229], 12, v[192:193]
	v_lshl_add_u64 v[244:245], s[36:37], 0, v[226:227]
	global_load_dwordx4 v[198:201], v[244:245], off offset:0
	global_load_dwordx4 v[202:205], v[244:245], off offset:64
	global_load_dwordx4 v[210:213], v[244:245], off offset:512
	global_load_dwordx4 v[214:217], v[244:245], off offset:576
	v_lshl_add_u64 v[242:243], s[12:13], 0, v[226:227]
	v_lshl_add_u64 v[242:243], v[242:243], 0, v[228:229]
	s_mov_b32 s31, 0
	s_mov_b32 s30, 0x0
	v_lshl_add_u64 v[246:247], v[242:243], 0, s[30:31]
	global_load_dwordx4 v[134:137], v[246:247], off offset:0
	global_load_dwordx4 v[138:141], v[246:247], off offset:64
	global_load_dwordx4 v[142:145], v[246:247], off offset:512
	global_load_dwordx4 v[146:149], v[246:247], off offset:576
	s_mov_b32 s30, 0x10000
	v_lshl_add_u64 v[246:247], v[242:243], 0, s[30:31]
	global_load_dwordx4 v[150:153], v[246:247], off offset:0
	global_load_dwordx4 v[154:157], v[246:247], off offset:64
	global_load_dwordx4 v[158:161], v[246:247], off offset:512
	global_load_dwordx4 v[162:165], v[246:247], off offset:576
	s_mov_b32 s30, 0x20000
	v_lshl_add_u64 v[246:247], v[242:243], 0, s[30:31]
	global_load_dwordx4 v[166:169], v[246:247], off offset:0
	global_load_dwordx4 v[170:173], v[246:247], off offset:64
	global_load_dwordx4 v[174:177], v[246:247], off offset:512
	global_load_dwordx4 v[178:181], v[246:247], off offset:576
	s_mov_b32 s30, 0x30000
	v_lshl_add_u64 v[246:247], v[242:243], 0, s[30:31]
	global_load_dwordx4 v[182:185], v[246:247], off offset:0
	global_load_dwordx4 v[186:189], v[246:247], off offset:64
	global_load_dwordx4 v[190:193], v[246:247], off offset:512
	global_load_dwordx4 v[194:197], v[246:247], off offset:576
	s_waitcnt vmcnt(0)
	v_pk_fma_f32 v[130:131], v[130:131], v[198:199], v[134:135]
	v_pk_fma_f32 v[132:133], v[132:133], v[200:201], v[136:137]
	v_pk_fma_f32 v[126:127], v[126:127], v[202:203], v[138:139]
	v_pk_fma_f32 v[128:129], v[128:129], v[204:205], v[140:141]
	v_pk_fma_f32 v[122:123], v[122:123], v[210:211], v[142:143]
	v_pk_fma_f32 v[124:125], v[124:125], v[212:213], v[144:145]
	v_pk_fma_f32 v[118:119], v[118:119], v[214:215], v[146:147]
	v_pk_fma_f32 v[120:121], v[120:121], v[216:217], v[148:149]
	v_pk_fma_f32 v[114:115], v[114:115], v[198:199], v[150:151]
	v_pk_fma_f32 v[116:117], v[116:117], v[200:201], v[152:153]
	v_pk_fma_f32 v[110:111], v[110:111], v[202:203], v[154:155]
	v_pk_fma_f32 v[112:113], v[112:113], v[204:205], v[156:157]
	v_pk_fma_f32 v[106:107], v[106:107], v[210:211], v[158:159]
	v_pk_fma_f32 v[108:109], v[108:109], v[212:213], v[160:161]
	v_pk_fma_f32 v[102:103], v[102:103], v[214:215], v[162:163]
	v_pk_fma_f32 v[104:105], v[104:105], v[216:217], v[164:165]
	v_pk_fma_f32 v[98:99], v[98:99], v[198:199], v[166:167]
	v_pk_fma_f32 v[100:101], v[100:101], v[200:201], v[168:169]
	v_pk_fma_f32 v[94:95], v[94:95], v[202:203], v[170:171]
	v_pk_fma_f32 v[96:97], v[96:97], v[204:205], v[172:173]
	v_pk_fma_f32 v[90:91], v[90:91], v[210:211], v[174:175]
	v_pk_fma_f32 v[92:93], v[92:93], v[212:213], v[176:177]
	v_pk_fma_f32 v[86:87], v[86:87], v[214:215], v[178:179]
	v_pk_fma_f32 v[88:89], v[88:89], v[216:217], v[180:181]
	v_pk_fma_f32 v[82:83], v[82:83], v[198:199], v[182:183]
	v_pk_fma_f32 v[84:85], v[84:85], v[200:201], v[184:185]
	v_pk_fma_f32 v[78:79], v[78:79], v[202:203], v[186:187]
	v_pk_fma_f32 v[80:81], v[80:81], v[204:205], v[188:189]
	v_pk_fma_f32 v[74:75], v[74:75], v[210:211], v[190:191]
	v_pk_fma_f32 v[76:77], v[76:77], v[212:213], v[192:193]
	v_pk_fma_f32 v[70:71], v[70:71], v[214:215], v[194:195]
	v_pk_fma_f32 v[72:73], v[72:73], v[216:217], v[196:197]
	s_mov_b32 s30, 0x80000
	v_lshl_add_u64 v[246:247], v[242:243], 0, s[30:31]
	global_load_dwordx4 v[134:137], v[246:247], off offset:0
	global_load_dwordx4 v[138:141], v[246:247], off offset:64
	global_load_dwordx4 v[142:145], v[246:247], off offset:512
	global_load_dwordx4 v[146:149], v[246:247], off offset:576
	s_mov_b32 s30, 0x90000
	v_lshl_add_u64 v[246:247], v[242:243], 0, s[30:31]
	global_load_dwordx4 v[150:153], v[246:247], off offset:0
	global_load_dwordx4 v[154:157], v[246:247], off offset:64
	global_load_dwordx4 v[158:161], v[246:247], off offset:512
	global_load_dwordx4 v[162:165], v[246:247], off offset:576
	s_mov_b32 s30, 0xa0000
	v_lshl_add_u64 v[246:247], v[242:243], 0, s[30:31]
	global_load_dwordx4 v[166:169], v[246:247], off offset:0
	global_load_dwordx4 v[170:173], v[246:247], off offset:64
	global_load_dwordx4 v[174:177], v[246:247], off offset:512
	global_load_dwordx4 v[178:181], v[246:247], off offset:576
	s_mov_b32 s30, 0xb0000
	v_lshl_add_u64 v[246:247], v[242:243], 0, s[30:31]
	global_load_dwordx4 v[182:185], v[246:247], off offset:0
	global_load_dwordx4 v[186:189], v[246:247], off offset:64
	global_load_dwordx4 v[190:193], v[246:247], off offset:512
	global_load_dwordx4 v[194:197], v[246:247], off offset:576
	s_waitcnt vmcnt(0)
	v_pk_fma_f32 v[66:67], v[66:67], v[198:199], v[134:135]
	v_pk_fma_f32 v[68:69], v[68:69], v[200:201], v[136:137]
	v_pk_fma_f32 v[62:63], v[62:63], v[202:203], v[138:139]
	v_pk_fma_f32 v[64:65], v[64:65], v[204:205], v[140:141]
	v_pk_fma_f32 v[58:59], v[58:59], v[210:211], v[142:143]
	v_pk_fma_f32 v[60:61], v[60:61], v[212:213], v[144:145]
	v_pk_fma_f32 v[54:55], v[54:55], v[214:215], v[146:147]
	v_pk_fma_f32 v[56:57], v[56:57], v[216:217], v[148:149]
	v_pk_fma_f32 v[50:51], v[50:51], v[198:199], v[150:151]
	v_pk_fma_f32 v[52:53], v[52:53], v[200:201], v[152:153]
	v_pk_fma_f32 v[46:47], v[46:47], v[202:203], v[154:155]
	v_pk_fma_f32 v[48:49], v[48:49], v[204:205], v[156:157]
	v_pk_fma_f32 v[42:43], v[42:43], v[210:211], v[158:159]
	v_pk_fma_f32 v[44:45], v[44:45], v[212:213], v[160:161]
	v_pk_fma_f32 v[38:39], v[38:39], v[214:215], v[162:163]
	v_pk_fma_f32 v[40:41], v[40:41], v[216:217], v[164:165]
	v_pk_fma_f32 v[34:35], v[34:35], v[198:199], v[166:167]
	v_pk_fma_f32 v[36:37], v[36:37], v[200:201], v[168:169]
	v_pk_fma_f32 v[30:31], v[30:31], v[202:203], v[170:171]
	v_pk_fma_f32 v[32:33], v[32:33], v[204:205], v[172:173]
	v_pk_fma_f32 v[26:27], v[26:27], v[210:211], v[174:175]
	v_pk_fma_f32 v[28:29], v[28:29], v[212:213], v[176:177]
	v_pk_fma_f32 v[22:23], v[22:23], v[214:215], v[178:179]
	v_pk_fma_f32 v[24:25], v[24:25], v[216:217], v[180:181]
	v_pk_fma_f32 v[18:19], v[18:19], v[198:199], v[182:183]
	v_pk_fma_f32 v[20:21], v[20:21], v[200:201], v[184:185]
	v_pk_fma_f32 v[14:15], v[14:15], v[202:203], v[186:187]
	v_pk_fma_f32 v[16:17], v[16:17], v[204:205], v[188:189]
	v_pk_fma_f32 v[10:11], v[10:11], v[210:211], v[190:191]
	v_pk_fma_f32 v[12:13], v[12:13], v[212:213], v[192:193]
	v_pk_fma_f32 v[6:7], v[6:7], v[214:215], v[194:195]
	v_pk_fma_f32 v[8:9], v[8:9], v[216:217], v[196:197]
	s_cmp_eq_u32 s38, 7
	s_cbranch_scc1 .Lrn_final_p
	s_and_b32 s25, s38, 1
	s_lshr_b32 s30, s38, 1
	s_cmp_eq_u32 s25, 0
	s_cbranch_scc1 .Lrn_ffn_p
	s_add_i32 s30, s30, 1
	s_movk_i32 s25, 0x48
	s_mul_i32 s31, s30, 0x6000
	s_branch .Lrn_p_done
.Lrn_ffn_p:
	s_movk_i32 s25, 0x50
	s_mul_i32 s31, s30, 0x6000
	s_add_i32 s31, s31, 0x3000
	s_branch .Lrn_p_done
.Lrn_final_p:
	s_movk_i32 s25, 0xd0
	s_mov_b32 s30, 0
	s_mov_b32 s31, 0
.Lrn_p_done:
	s_load_dwordx2 s[36:37], s[54:55], s25
	s_lshl_b32 s30, s30, 12
	s_waitcnt lgkmcnt(0)
	s_add_u32 s36, s36, s30
	s_addc_u32 s37, s37, 0
	v_lshl_add_u64 v[246:247], s[36:37], 0, v[226:227]
	global_load_dwordx4 v[134:137], v[246:247], off offset:0
	global_load_dwordx4 v[138:141], v[246:247], off offset:64
	global_load_dwordx4 v[142:145], v[246:247], off offset:512
	global_load_dwordx4 v[146:149], v[246:247], off offset:576
	v_mov_b32_e32 v150, 0
	v_mov_b32_e32 v166, 0
	v_mov_b32_e32 v151, 0
	v_mov_b32_e32 v167, 0
	v_mov_b32_e32 v152, 0
	v_mov_b32_e32 v168, 0
	v_mov_b32_e32 v153, 0
	v_mov_b32_e32 v169, 0
	v_mov_b32_e32 v154, 0
	v_mov_b32_e32 v170, 0
	v_mov_b32_e32 v155, 0
	v_mov_b32_e32 v171, 0
	v_mov_b32_e32 v156, 0
	v_mov_b32_e32 v172, 0
	v_mov_b32_e32 v157, 0
	v_mov_b32_e32 v173, 0
	v_mov_b32_e32 v158, 0
	v_mov_b32_e32 v174, 0
	v_mov_b32_e32 v159, 0
	v_mov_b32_e32 v175, 0
	v_mov_b32_e32 v160, 0
	v_mov_b32_e32 v176, 0
	v_mov_b32_e32 v161, 0
	v_mov_b32_e32 v177, 0
	v_mov_b32_e32 v162, 0
	v_mov_b32_e32 v178, 0
	v_mov_b32_e32 v163, 0
	v_mov_b32_e32 v179, 0
	v_mov_b32_e32 v164, 0
	v_mov_b32_e32 v180, 0
	v_mov_b32_e32 v165, 0
	v_mov_b32_e32 v181, 0
	s_cmp_eq_u32 s38, 7
	s_cbranch_scc1 .Lrn_nomod
	v_readlane_b32 s36, v253, 34
	v_readlane_b32 s37, v253, 35
	s_ashr_i32 s25, s76, 5
	s_mul_i32 s25, s25, 0x18000
	s_add_i32 s25, s25, s31
	s_add_u32 s36, s36, s25
	s_addc_u32 s37, s37, 0
	v_lshl_add_u64 v[248:249], s[36:37], 0, v[226:227]
	global_load_dwordx4 v[150:153], v[248:249], off offset:0
	global_load_dwordx4 v[154:157], v[248:249], off offset:64
	global_load_dwordx4 v[158:161], v[248:249], off offset:512
	global_load_dwordx4 v[162:165], v[248:249], off offset:576
	s_movk_i32 s30, 0x1000
	s_mov_b32 s31, 0
	v_lshl_add_u64 v[248:249], v[248:249], 0, s[30:31]
	global_load_dwordx4 v[166:169], v[248:249], off offset:0
	global_load_dwordx4 v[170:173], v[248:249], off offset:64
	global_load_dwordx4 v[174:177], v[248:249], off offset:512
	global_load_dwordx4 v[178:181], v[248:249], off offset:576
.Lrn_nomod:
	v_pk_mul_f32 v[220:221], v[130:131], v[130:131]
	v_pk_fma_f32 v[220:221], v[132:133], v[132:133], v[220:221]
	v_pk_fma_f32 v[220:221], v[126:127], v[126:127], v[220:221]
	v_pk_fma_f32 v[220:221], v[128:129], v[128:129], v[220:221]
	v_pk_fma_f32 v[220:221], v[122:123], v[122:123], v[220:221]
	v_pk_fma_f32 v[220:221], v[124:125], v[124:125], v[220:221]
	v_pk_fma_f32 v[220:221], v[118:119], v[118:119], v[220:221]
	v_pk_fma_f32 v[220:221], v[120:121], v[120:121], v[220:221]
	v_add_f32_e32 v182, v220, v221
	v_pk_mul_f32 v[220:221], v[114:115], v[114:115]
	v_pk_fma_f32 v[220:221], v[116:117], v[116:117], v[220:221]
	v_pk_fma_f32 v[220:221], v[110:111], v[110:111], v[220:221]
	v_pk_fma_f32 v[220:221], v[112:113], v[112:113], v[220:221]
	v_pk_fma_f32 v[220:221], v[106:107], v[106:107], v[220:221]
	v_pk_fma_f32 v[220:221], v[108:109], v[108:109], v[220:221]
	v_pk_fma_f32 v[220:221], v[102:103], v[102:103], v[220:221]
	v_pk_fma_f32 v[220:221], v[104:105], v[104:105], v[220:221]
	v_add_f32_e32 v184, v220, v221
	v_pk_mul_f32 v[220:221], v[98:99], v[98:99]
	v_pk_fma_f32 v[220:221], v[100:101], v[100:101], v[220:221]
	v_pk_fma_f32 v[220:221], v[94:95], v[94:95], v[220:221]
	v_pk_fma_f32 v[220:221], v[96:97], v[96:97], v[220:221]
	v_pk_fma_f32 v[220:221], v[90:91], v[90:91], v[220:221]
	v_pk_fma_f32 v[220:221], v[92:93], v[92:93], v[220:221]
	v_pk_fma_f32 v[220:221], v[86:87], v[86:87], v[220:221]
	v_pk_fma_f32 v[220:221], v[88:89], v[88:89], v[220:221]
	v_add_f32_e32 v186, v220, v221
	v_pk_mul_f32 v[220:221], v[82:83], v[82:83]
	v_pk_fma_f32 v[220:221], v[84:85], v[84:85], v[220:221]
	v_pk_fma_f32 v[220:221], v[78:79], v[78:79], v[220:221]
	v_pk_fma_f32 v[220:221], v[80:81], v[80:81], v[220:221]
	v_pk_fma_f32 v[220:221], v[74:75], v[74:75], v[220:221]
	v_pk_fma_f32 v[220:221], v[76:77], v[76:77], v[220:221]
	v_pk_fma_f32 v[220:221], v[70:71], v[70:71], v[220:221]
	v_pk_fma_f32 v[220:221], v[72:73], v[72:73], v[220:221]
	v_add_f32_e32 v188, v220, v221
	v_pk_mul_f32 v[220:221], v[66:67], v[66:67]
	v_pk_fma_f32 v[220:221], v[68:69], v[68:69], v[220:221]
	v_pk_fma_f32 v[220:221], v[62:63], v[62:63], v[220:221]
	v_pk_fma_f32 v[220:221], v[64:65], v[64:65], v[220:221]
	v_pk_fma_f32 v[220:221], v[58:59], v[58:59], v[220:221]
	v_pk_fma_f32 v[220:221], v[60:61], v[60:61], v[220:221]
	v_pk_fma_f32 v[220:221], v[54:55], v[54:55], v[220:221]
	v_pk_fma_f32 v[220:221], v[56:57], v[56:57], v[220:221]
	v_add_f32_e32 v190, v220, v221
	v_pk_mul_f32 v[220:221], v[50:51], v[50:51]
	v_pk_fma_f32 v[220:221], v[52:53], v[52:53], v[220:221]
	v_pk_fma_f32 v[220:221], v[46:47], v[46:47], v[220:221]
	v_pk_fma_f32 v[220:221], v[48:49], v[48:49], v[220:221]
	v_pk_fma_f32 v[220:221], v[42:43], v[42:43], v[220:221]
	v_pk_fma_f32 v[220:221], v[44:45], v[44:45], v[220:221]
	v_pk_fma_f32 v[220:221], v[38:39], v[38:39], v[220:221]
	v_pk_fma_f32 v[220:221], v[40:41], v[40:41], v[220:221]
	v_add_f32_e32 v192, v220, v221
	v_pk_mul_f32 v[220:221], v[34:35], v[34:35]
	v_pk_fma_f32 v[220:221], v[36:37], v[36:37], v[220:221]
	v_pk_fma_f32 v[220:221], v[30:31], v[30:31], v[220:221]
	v_pk_fma_f32 v[220:221], v[32:33], v[32:33], v[220:221]
	v_pk_fma_f32 v[220:221], v[26:27], v[26:27], v[220:221]
	v_pk_fma_f32 v[220:221], v[28:29], v[28:29], v[220:221]
	v_pk_fma_f32 v[220:221], v[22:23], v[22:23], v[220:221]
	v_pk_fma_f32 v[220:221], v[24:25], v[24:25], v[220:221]
	v_add_f32_e32 v194, v220, v221
	v_pk_mul_f32 v[220:221], v[18:19], v[18:19]
	v_pk_fma_f32 v[220:221], v[20:21], v[20:21], v[220:221]
	v_pk_fma_f32 v[220:221], v[14:15], v[14:15], v[220:221]
	v_pk_fma_f32 v[220:221], v[16:17], v[16:17], v[220:221]
	v_pk_fma_f32 v[220:221], v[10:11], v[10:11], v[220:221]
	v_pk_fma_f32 v[220:221], v[12:13], v[12:13], v[220:221]
	v_pk_fma_f32 v[220:221], v[6:7], v[6:7], v[220:221]
	v_pk_fma_f32 v[220:221], v[8:9], v[8:9], v[220:221]
	v_add_f32_e32 v196, v220, v221
	v_add_f32_dpp v182, v182, v182 quad_perm:[1,0,3,2] row_mask:0xf bank_mask:0xf
	v_add_f32_dpp v184, v184, v184 quad_perm:[1,0,3,2] row_mask:0xf bank_mask:0xf
	v_add_f32_dpp v186, v186, v186 quad_perm:[1,0,3,2] row_mask:0xf bank_mask:0xf
	v_add_f32_dpp v188, v188, v188 quad_perm:[1,0,3,2] row_mask:0xf bank_mask:0xf
	v_add_f32_dpp v190, v190, v190 quad_perm:[1,0,3,2] row_mask:0xf bank_mask:0xf
	v_add_f32_dpp v192, v192, v192 quad_perm:[1,0,3,2] row_mask:0xf bank_mask:0xf
	v_add_f32_dpp v194, v194, v194 quad_perm:[1,0,3,2] row_mask:0xf bank_mask:0xf
	v_add_f32_dpp v196, v196, v196 quad_perm:[1,0,3,2] row_mask:0xf bank_mask:0xf
	v_add_f32_dpp v182, v182, v182 quad_perm:[2,3,0,1] row_mask:0xf bank_mask:0xf
	v_add_f32_dpp v184, v184, v184 quad_perm:[2,3,0,1] row_mask:0xf bank_mask:0xf
	v_add_f32_dpp v186, v186, v186 quad_perm:[2,3,0,1] row_mask:0xf bank_mask:0xf
	v_add_f32_dpp v188, v188, v188 quad_perm:[2,3,0,1] row_mask:0xf bank_mask:0xf
	v_add_f32_dpp v190, v190, v190 quad_perm:[2,3,0,1] row_mask:0xf bank_mask:0xf
	v_add_f32_dpp v192, v192, v192 quad_perm:[2,3,0,1] row_mask:0xf bank_mask:0xf
	v_add_f32_dpp v194, v194, v194 quad_perm:[2,3,0,1] row_mask:0xf bank_mask:0xf
	v_add_f32_dpp v196, v196, v196 quad_perm:[2,3,0,1] row_mask:0xf bank_mask:0xf
	v_and_b32_e32 v210, 0x60, v225
	v_lshlrev_b32_e32 v210, 5, v210
	v_add_u32_e32 v211, s62, v223
	v_lshl_add_u32 v210, v211, 2, v210
	v_add_u32_e32 v210, 0x21000, v210
	s_mov_b32 exec_lo, 0x11111111
	s_mov_b32 exec_hi, 0x11111111
	ds_write_b32 v210, v182 offset:0
	ds_write_b32 v210, v184 offset:64
	ds_write_b32 v210, v186 offset:128
	ds_write_b32 v210, v188 offset:192
	ds_write_b32 v210, v190 offset:512
	ds_write_b32 v210, v192 offset:576
	ds_write_b32 v210, v194 offset:640
	ds_write_b32 v210, v196 offset:704
	s_mov_b64 exec, -1
	s_waitcnt lgkmcnt(0)
	s_barrier
	v_readfirstlane_b32 s25, v230
	s_lshr_b32 s25, s25, 6
	v_readlane_b32 s36, v253, 42
	v_readlane_b32 s37, v253, 43
	s_lshl_b32 s30, s38, 6
	s_add_i32 s30, s30, s76
	s_lshl_b32 s31, s30, 12
	s_add_u32 s36, s36, s31
	s_addc_u32 s37, s37, 0
	s_add_u32 s36, s36, 0x9c00000
	s_addc_u32 s37, s37, 0
	s_cmp_gt_u32 s25, 3
	s_cbranch_scc1 .Lrn_noslot
	v_lshlrev_b32_e32 v211, 2, v230
	v_add_u32_e32 v210, 0x21000, v211
	ds_read_b32 v216, v210
	ds_read_b32 v217, v210 offset:1024
	ds_read_b32 v220, v210 offset:2048
	ds_read_b32 v221, v210 offset:3072
	s_lshl_b32 s31, s77, 10
	v_add_u32_e32 v210, s31, v211
	s_waitcnt lgkmcnt(0)
	v_add_f32_e32 v216, v216, v217
	v_add_f32_e32 v216, v216, v220
	v_add_f32_e32 v216, v216, v221
	global_store_dword v210, v216, s[36:37] sc1
.Lrn_noslot:
	s_waitcnt vmcnt(0)
	s_barrier
	s_cmp_lg_u32 s25, 0
	s_cbranch_scc1 .Lrn_nopoll
	v_readlane_b32 s30, v253, 42
	v_readlane_b32 s31, v253, 43
	s_lshl_b32 s25, s38, 6
	s_add_i32 s25, s25, s76
	s_lshl_b32 s25, s25, 2
	s_add_i32 s25, s25, 0x8000
	s_add_u32 s30, s30, s25
	s_addc_u32 s31, s31, 0
	s_mov_b64 exec, 1
	v_mov_b32_e32 v216, 1
	s_nop 4
	global_atomic_add v1, v216, s[30:31]
	s_mov_b32 s25, 0
.Lrn_poll:
	s_sleep 1
	global_load_dword v216, v1, s[30:31] sc1
	s_waitcnt vmcnt(0)
	v_readfirstlane_b32 vcc_lo, v216
	s_cmp_gt_u32 vcc_lo, 3
	s_cbranch_scc1 .Lrn_polled
	s_add_i32 s25, s25, 1
	s_cmp_lt_u32 s25, 0x10000
	s_cbranch_scc1 .Lrn_poll
.Lrn_polled:
	s_mov_b64 exec, -1
	s_mov_b32 s25, 0
.Lrn_nopoll:
	s_barrier
	s_cmp_gt_u32 s25, 3
	s_cbranch_scc1 .Lrn_nors
	global_load_dword v216, v211, s[36:37] sc1
	global_load_dword v217, v211, s[36:37] offset:1024 sc1
	global_load_dword v220, v211, s[36:37] offset:2048 sc1
	global_load_dword v221, v211, s[36:37] offset:3072 sc1
	v_add_u32_e32 v210, 0x22000, v211
	s_waitcnt vmcnt(0)
	v_add_f32_e32 v216, v216, v217
	v_add_f32_e32 v216, v216, v220
	v_add_f32_e32 v216, v216, v221
	v_fmamk_f32 v216, v216, 0x3a800000, v232
	v_rsq_f32_e32 v216, v216
	s_nop 0
	ds_write_b32 v210, v216
.Lrn_nors:
	s_waitcnt lgkmcnt(0)
	s_barrier
	v_add_u32_e32 v211, s62, v223
	v_lshlrev_b32_e32 v210, 2, v211
	v_add_u32_e32 v210, 0x22000, v210
	ds_read_b32 v182, v210 offset:0
	ds_read_b32 v184, v210 offset:64
	ds_read_b32 v186, v210 offset:128
	ds_read_b32 v188, v210 offset:192
	ds_read_b32 v190, v210 offset:512
	ds_read_b32 v192, v210 offset:576
	ds_read_b32 v194, v210 offset:640
	ds_read_b32 v196, v210 offset:704
	v_pk_add_f32 v[166:167], v[166:167], 1.0 op_sel_hi:[1,0]
	v_pk_mul_f32 v[134:135], v[134:135], v[166:167]
	v_pk_add_f32 v[168:169], v[168:169], 1.0 op_sel_hi:[1,0]
	v_pk_mul_f32 v[136:137], v[136:137], v[168:169]
	v_pk_add_f32 v[170:171], v[170:171], 1.0 op_sel_hi:[1,0]
	v_pk_mul_f32 v[138:139], v[138:139], v[170:171]
	v_pk_add_f32 v[172:173], v[172:173], 1.0 op_sel_hi:[1,0]
	v_pk_mul_f32 v[140:141], v[140:141], v[172:173]
	v_pk_add_f32 v[174:175], v[174:175], 1.0 op_sel_hi:[1,0]
	v_pk_mul_f32 v[142:143], v[142:143], v[174:175]
	v_pk_add_f32 v[176:177], v[176:177], 1.0 op_sel_hi:[1,0]
	v_pk_mul_f32 v[144:145], v[144:145], v[176:177]
	v_pk_add_f32 v[178:179], v[178:179], 1.0 op_sel_hi:[1,0]
	v_pk_mul_f32 v[146:147], v[146:147], v[178:179]
	v_pk_add_f32 v[180:181], v[180:181], 1.0 op_sel_hi:[1,0]
	v_pk_mul_f32 v[148:149], v[148:149], v[180:181]
	v_lshl_add_u64 v[242:243], s[10:11], 0, v[226:227]
	v_lshl_add_u64 v[242:243], v[242:243], 0, v[228:229]
	v_readlane_b32 s36, v253, 42
	v_readlane_b32 s37, v253, 43
	s_add_u32 s36, s36, 0x7400000
	s_addc_u32 s37, s37, 0
	v_lshrrev_b64 v[244:245], 1, v[226:227]
	v_lshrrev_b64 v[246:247], 1, v[228:229]
	v_lshl_add_u64 v[244:245], s[36:37], 0, v[244:245]
	v_lshl_add_u64 v[244:245], v[244:245], 0, v[246:247]
	s_mov_b32 s31, 0
	s_waitcnt lgkmcnt(0)
	s_cmp_eq_u32 s38, 7
	s_cbranch_scc1 .Lrn_final_out
	s_mov_b32 s30, 0x0
	v_lshl_add_u64 v[246:247], v[242:243], 0, s[30:31]
	s_mov_b32 s30, 0x0
	v_lshl_add_u64 v[248:249], v[244:245], 0, s[30:31]
	global_store_dwordx4 v[246:247], v[130:133], off offset:0
	v_pk_mul_f32 v[198:199], v[130:131], v[182:183] op_sel_hi:[1,0]
	v_pk_fma_f32 v[198:199], v[198:199], v[134:135], v[150:151]
	v_pk_mul_f32 v[200:201], v[132:133], v[182:183] op_sel_hi:[1,0]
	v_pk_fma_f32 v[200:201], v[200:201], v[136:137], v[152:153]
	v_cvt_pk_bf16_f32 v214, v198, v199
	v_cvt_pk_bf16_f32 v215, v200, v201
	global_store_dwordx2 v[248:249], v[214:215], off offset:0
	global_store_dwordx4 v[246:247], v[126:129], off offset:64
	v_pk_mul_f32 v[202:203], v[126:127], v[182:183] op_sel_hi:[1,0]
	v_pk_fma_f32 v[202:203], v[202:203], v[138:139], v[154:155]
	v_pk_mul_f32 v[204:205], v[128:129], v[182:183] op_sel_hi:[1,0]
	v_pk_fma_f32 v[204:205], v[204:205], v[140:141], v[156:157]
	v_cvt_pk_bf16_f32 v216, v202, v203
	v_cvt_pk_bf16_f32 v217, v204, v205
	global_store_dwordx2 v[248:249], v[216:217], off offset:32
	global_store_dwordx4 v[246:247], v[122:125], off offset:512
	v_pk_mul_f32 v[198:199], v[122:123], v[182:183] op_sel_hi:[1,0]
	v_pk_fma_f32 v[198:199], v[198:199], v[142:143], v[158:159]
	v_pk_mul_f32 v[200:201], v[124:125], v[182:183] op_sel_hi:[1,0]
	v_pk_fma_f32 v[200:201], v[200:201], v[144:145], v[160:161]
	v_cvt_pk_bf16_f32 v214, v198, v199
	v_cvt_pk_bf16_f32 v215, v200, v201
	global_store_dwordx2 v[248:249], v[214:215], off offset:256
	global_store_dwordx4 v[246:247], v[118:121], off offset:576
	v_pk_mul_f32 v[202:203], v[118:119], v[182:183] op_sel_hi:[1,0]
	v_pk_fma_f32 v[202:203], v[202:203], v[146:147], v[162:163]
	v_pk_mul_f32 v[204:205], v[120:121], v[182:183] op_sel_hi:[1,0]
	v_pk_fma_f32 v[204:205], v[204:205], v[148:149], v[164:165]
	v_cvt_pk_bf16_f32 v216, v202, v203
	v_cvt_pk_bf16_f32 v217, v204, v205
	global_store_dwordx2 v[248:249], v[216:217], off offset:288
	s_mov_b32 s30, 0x10000
	v_lshl_add_u64 v[246:247], v[242:243], 0, s[30:31]
	s_mov_b32 s30, 0x8000
	v_lshl_add_u64 v[248:249], v[244:245], 0, s[30:31]
	global_store_dwordx4 v[246:247], v[114:117], off offset:0
	v_pk_mul_f32 v[198:199], v[114:115], v[184:185] op_sel_hi:[1,0]
	v_pk_fma_f32 v[198:199], v[198:199], v[134:135], v[150:151]
	v_pk_mul_f32 v[200:201], v[116:117], v[184:185] op_sel_hi:[1,0]
	v_pk_fma_f32 v[200:201], v[200:201], v[136:137], v[152:153]
	v_cvt_pk_bf16_f32 v214, v198, v199
	v_cvt_pk_bf16_f32 v215, v200, v201
	global_store_dwordx2 v[248:249], v[214:215], off offset:0
	global_store_dwordx4 v[246:247], v[110:113], off offset:64
	v_pk_mul_f32 v[202:203], v[110:111], v[184:185] op_sel_hi:[1,0]
	v_pk_fma_f32 v[202:203], v[202:203], v[138:139], v[154:155]
	v_pk_mul_f32 v[204:205], v[112:113], v[184:185] op_sel_hi:[1,0]
	v_pk_fma_f32 v[204:205], v[204:205], v[140:141], v[156:157]
	v_cvt_pk_bf16_f32 v216, v202, v203
	v_cvt_pk_bf16_f32 v217, v204, v205
	global_store_dwordx2 v[248:249], v[216:217], off offset:32
	global_store_dwordx4 v[246:247], v[106:109], off offset:512
	v_pk_mul_f32 v[198:199], v[106:107], v[184:185] op_sel_hi:[1,0]
	v_pk_fma_f32 v[198:199], v[198:199], v[142:143], v[158:159]
	v_pk_mul_f32 v[200:201], v[108:109], v[184:185] op_sel_hi:[1,0]
	v_pk_fma_f32 v[200:201], v[200:201], v[144:145], v[160:161]
	v_cvt_pk_bf16_f32 v214, v198, v199
	v_cvt_pk_bf16_f32 v215, v200, v201
	global_store_dwordx2 v[248:249], v[214:215], off offset:256
	global_store_dwordx4 v[246:247], v[102:105], off offset:576
	v_pk_mul_f32 v[202:203], v[102:103], v[184:185] op_sel_hi:[1,0]
	v_pk_fma_f32 v[202:203], v[202:203], v[146:147], v[162:163]
	v_pk_mul_f32 v[204:205], v[104:105], v[184:185] op_sel_hi:[1,0]
	v_pk_fma_f32 v[204:205], v[204:205], v[148:149], v[164:165]
	v_cvt_pk_bf16_f32 v216, v202, v203
	v_cvt_pk_bf16_f32 v217, v204, v205
	global_store_dwordx2 v[248:249], v[216:217], off offset:288
	s_mov_b32 s30, 0x20000
	v_lshl_add_u64 v[246:247], v[242:243], 0, s[30:31]
	s_mov_b32 s30, 0x10000
	v_lshl_add_u64 v[248:249], v[244:245], 0, s[30:31]
	global_store_dwordx4 v[246:247], v[98:101], off offset:0
	v_pk_mul_f32 v[198:199], v[98:99], v[186:187] op_sel_hi:[1,0]
	v_pk_fma_f32 v[198:199], v[198:199], v[134:135], v[150:151]
	v_pk_mul_f32 v[200:201], v[100:101], v[186:187] op_sel_hi:[1,0]
	v_pk_fma_f32 v[200:201], v[200:201], v[136:137], v[152:153]
	v_cvt_pk_bf16_f32 v214, v198, v199
	v_cvt_pk_bf16_f32 v215, v200, v201
	global_store_dwordx2 v[248:249], v[214:215], off offset:0
	global_store_dwordx4 v[246:247], v[94:97], off offset:64
	v_pk_mul_f32 v[202:203], v[94:95], v[186:187] op_sel_hi:[1,0]
	v_pk_fma_f32 v[202:203], v[202:203], v[138:139], v[154:155]
	v_pk_mul_f32 v[204:205], v[96:97], v[186:187] op_sel_hi:[1,0]
	v_pk_fma_f32 v[204:205], v[204:205], v[140:141], v[156:157]
	v_cvt_pk_bf16_f32 v216, v202, v203
	v_cvt_pk_bf16_f32 v217, v204, v205
	global_store_dwordx2 v[248:249], v[216:217], off offset:32
	global_store_dwordx4 v[246:247], v[90:93], off offset:512
	v_pk_mul_f32 v[198:199], v[90:91], v[186:187] op_sel_hi:[1,0]
	v_pk_fma_f32 v[198:199], v[198:199], v[142:143], v[158:159]
	v_pk_mul_f32 v[200:201], v[92:93], v[186:187] op_sel_hi:[1,0]
	v_pk_fma_f32 v[200:201], v[200:201], v[144:145], v[160:161]
	v_cvt_pk_bf16_f32 v214, v198, v199
	v_cvt_pk_bf16_f32 v215, v200, v201
	global_store_dwordx2 v[248:249], v[214:215], off offset:256
	global_store_dwordx4 v[246:247], v[86:89], off offset:576
	v_pk_mul_f32 v[202:203], v[86:87], v[186:187] op_sel_hi:[1,0]
	v_pk_fma_f32 v[202:203], v[202:203], v[146:147], v[162:163]
	v_pk_mul_f32 v[204:205], v[88:89], v[186:187] op_sel_hi:[1,0]
	v_pk_fma_f32 v[204:205], v[204:205], v[148:149], v[164:165]
	v_cvt_pk_bf16_f32 v216, v202, v203
	v_cvt_pk_bf16_f32 v217, v204, v205
	global_store_dwordx2 v[248:249], v[216:217], off offset:288
	s_mov_b32 s30, 0x30000
	v_lshl_add_u64 v[246:247], v[242:243], 0, s[30:31]
	s_mov_b32 s30, 0x18000
	v_lshl_add_u64 v[248:249], v[244:245], 0, s[30:31]
	global_store_dwordx4 v[246:247], v[82:85], off offset:0
	v_pk_mul_f32 v[198:199], v[82:83], v[188:189] op_sel_hi:[1,0]
	v_pk_fma_f32 v[198:199], v[198:199], v[134:135], v[150:151]
	v_pk_mul_f32 v[200:201], v[84:85], v[188:189] op_sel_hi:[1,0]
	v_pk_fma_f32 v[200:201], v[200:201], v[136:137], v[152:153]
	v_cvt_pk_bf16_f32 v214, v198, v199
	v_cvt_pk_bf16_f32 v215, v200, v201
	global_store_dwordx2 v[248:249], v[214:215], off offset:0
	global_store_dwordx4 v[246:247], v[78:81], off offset:64
	v_pk_mul_f32 v[202:203], v[78:79], v[188:189] op_sel_hi:[1,0]
	v_pk_fma_f32 v[202:203], v[202:203], v[138:139], v[154:155]
	v_pk_mul_f32 v[204:205], v[80:81], v[188:189] op_sel_hi:[1,0]
	v_pk_fma_f32 v[204:205], v[204:205], v[140:141], v[156:157]
	v_cvt_pk_bf16_f32 v216, v202, v203
	v_cvt_pk_bf16_f32 v217, v204, v205
	global_store_dwordx2 v[248:249], v[216:217], off offset:32
	global_store_dwordx4 v[246:247], v[74:77], off offset:512
	v_pk_mul_f32 v[198:199], v[74:75], v[188:189] op_sel_hi:[1,0]
	v_pk_fma_f32 v[198:199], v[198:199], v[142:143], v[158:159]
	v_pk_mul_f32 v[200:201], v[76:77], v[188:189] op_sel_hi:[1,0]
	v_pk_fma_f32 v[200:201], v[200:201], v[144:145], v[160:161]
	v_cvt_pk_bf16_f32 v214, v198, v199
	v_cvt_pk_bf16_f32 v215, v200, v201
	global_store_dwordx2 v[248:249], v[214:215], off offset:256
	global_store_dwordx4 v[246:247], v[70:73], off offset:576
	v_pk_mul_f32 v[202:203], v[70:71], v[188:189] op_sel_hi:[1,0]
	v_pk_fma_f32 v[202:203], v[202:203], v[146:147], v[162:163]
	v_pk_mul_f32 v[204:205], v[72:73], v[188:189] op_sel_hi:[1,0]
	v_pk_fma_f32 v[204:205], v[204:205], v[148:149], v[164:165]
	v_cvt_pk_bf16_f32 v216, v202, v203
	v_cvt_pk_bf16_f32 v217, v204, v205
	global_store_dwordx2 v[248:249], v[216:217], off offset:288
	s_mov_b32 s30, 0x80000
	v_lshl_add_u64 v[246:247], v[242:243], 0, s[30:31]
	s_mov_b32 s30, 0x40000
	v_lshl_add_u64 v[248:249], v[244:245], 0, s[30:31]
	global_store_dwordx4 v[246:247], v[66:69], off offset:0
	v_pk_mul_f32 v[198:199], v[66:67], v[190:191] op_sel_hi:[1,0]
	v_pk_fma_f32 v[198:199], v[198:199], v[134:135], v[150:151]
	v_pk_mul_f32 v[200:201], v[68:69], v[190:191] op_sel_hi:[1,0]
	v_pk_fma_f32 v[200:201], v[200:201], v[136:137], v[152:153]
	v_cvt_pk_bf16_f32 v214, v198, v199
	v_cvt_pk_bf16_f32 v215, v200, v201
	global_store_dwordx2 v[248:249], v[214:215], off offset:0
	global_store_dwordx4 v[246:247], v[62:65], off offset:64
	v_pk_mul_f32 v[202:203], v[62:63], v[190:191] op_sel_hi:[1,0]
	v_pk_fma_f32 v[202:203], v[202:203], v[138:139], v[154:155]
	v_pk_mul_f32 v[204:205], v[64:65], v[190:191] op_sel_hi:[1,0]
	v_pk_fma_f32 v[204:205], v[204:205], v[140:141], v[156:157]
	v_cvt_pk_bf16_f32 v216, v202, v203
	v_cvt_pk_bf16_f32 v217, v204, v205
	global_store_dwordx2 v[248:249], v[216:217], off offset:32
	global_store_dwordx4 v[246:247], v[58:61], off offset:512
	v_pk_mul_f32 v[198:199], v[58:59], v[190:191] op_sel_hi:[1,0]
	v_pk_fma_f32 v[198:199], v[198:199], v[142:143], v[158:159]
	v_pk_mul_f32 v[200:201], v[60:61], v[190:191] op_sel_hi:[1,0]
	v_pk_fma_f32 v[200:201], v[200:201], v[144:145], v[160:161]
	v_cvt_pk_bf16_f32 v214, v198, v199
	v_cvt_pk_bf16_f32 v215, v200, v201
	global_store_dwordx2 v[248:249], v[214:215], off offset:256
	global_store_dwordx4 v[246:247], v[54:57], off offset:576
	v_pk_mul_f32 v[202:203], v[54:55], v[190:191] op_sel_hi:[1,0]
	v_pk_fma_f32 v[202:203], v[202:203], v[146:147], v[162:163]
	v_pk_mul_f32 v[204:205], v[56:57], v[190:191] op_sel_hi:[1,0]
	v_pk_fma_f32 v[204:205], v[204:205], v[148:149], v[164:165]
	v_cvt_pk_bf16_f32 v216, v202, v203
	v_cvt_pk_bf16_f32 v217, v204, v205
	global_store_dwordx2 v[248:249], v[216:217], off offset:288
	s_mov_b32 s30, 0x90000
	v_lshl_add_u64 v[246:247], v[242:243], 0, s[30:31]
	s_mov_b32 s30, 0x48000
	v_lshl_add_u64 v[248:249], v[244:245], 0, s[30:31]
	global_store_dwordx4 v[246:247], v[50:53], off offset:0
	v_pk_mul_f32 v[198:199], v[50:51], v[192:193] op_sel_hi:[1,0]
	v_pk_fma_f32 v[198:199], v[198:199], v[134:135], v[150:151]
	v_pk_mul_f32 v[200:201], v[52:53], v[192:193] op_sel_hi:[1,0]
	v_pk_fma_f32 v[200:201], v[200:201], v[136:137], v[152:153]
	v_cvt_pk_bf16_f32 v214, v198, v199
	v_cvt_pk_bf16_f32 v215, v200, v201
	global_store_dwordx2 v[248:249], v[214:215], off offset:0
	global_store_dwordx4 v[246:247], v[46:49], off offset:64
	v_pk_mul_f32 v[202:203], v[46:47], v[192:193] op_sel_hi:[1,0]
	v_pk_fma_f32 v[202:203], v[202:203], v[138:139], v[154:155]
	v_pk_mul_f32 v[204:205], v[48:49], v[192:193] op_sel_hi:[1,0]
	v_pk_fma_f32 v[204:205], v[204:205], v[140:141], v[156:157]
	v_cvt_pk_bf16_f32 v216, v202, v203
	v_cvt_pk_bf16_f32 v217, v204, v205
	global_store_dwordx2 v[248:249], v[216:217], off offset:32
	global_store_dwordx4 v[246:247], v[42:45], off offset:512
	v_pk_mul_f32 v[198:199], v[42:43], v[192:193] op_sel_hi:[1,0]
	v_pk_fma_f32 v[198:199], v[198:199], v[142:143], v[158:159]
	v_pk_mul_f32 v[200:201], v[44:45], v[192:193] op_sel_hi:[1,0]
	v_pk_fma_f32 v[200:201], v[200:201], v[144:145], v[160:161]
	v_cvt_pk_bf16_f32 v214, v198, v199
	v_cvt_pk_bf16_f32 v215, v200, v201
	global_store_dwordx2 v[248:249], v[214:215], off offset:256
	global_store_dwordx4 v[246:247], v[38:41], off offset:576
	v_pk_mul_f32 v[202:203], v[38:39], v[192:193] op_sel_hi:[1,0]
	v_pk_fma_f32 v[202:203], v[202:203], v[146:147], v[162:163]
	v_pk_mul_f32 v[204:205], v[40:41], v[192:193] op_sel_hi:[1,0]
	v_pk_fma_f32 v[204:205], v[204:205], v[148:149], v[164:165]
	v_cvt_pk_bf16_f32 v216, v202, v203
	v_cvt_pk_bf16_f32 v217, v204, v205
	global_store_dwordx2 v[248:249], v[216:217], off offset:288
	s_mov_b32 s30, 0xa0000
	v_lshl_add_u64 v[246:247], v[242:243], 0, s[30:31]
	s_mov_b32 s30, 0x50000
	v_lshl_add_u64 v[248:249], v[244:245], 0, s[30:31]
	global_store_dwordx4 v[246:247], v[34:37], off offset:0
	v_pk_mul_f32 v[198:199], v[34:35], v[194:195] op_sel_hi:[1,0]
	v_pk_fma_f32 v[198:199], v[198:199], v[134:135], v[150:151]
	v_pk_mul_f32 v[200:201], v[36:37], v[194:195] op_sel_hi:[1,0]
	v_pk_fma_f32 v[200:201], v[200:201], v[136:137], v[152:153]
	v_cvt_pk_bf16_f32 v214, v198, v199
	v_cvt_pk_bf16_f32 v215, v200, v201
	global_store_dwordx2 v[248:249], v[214:215], off offset:0
	global_store_dwordx4 v[246:247], v[30:33], off offset:64
	v_pk_mul_f32 v[202:203], v[30:31], v[194:195] op_sel_hi:[1,0]
	v_pk_fma_f32 v[202:203], v[202:203], v[138:139], v[154:155]
	v_pk_mul_f32 v[204:205], v[32:33], v[194:195] op_sel_hi:[1,0]
	v_pk_fma_f32 v[204:205], v[204:205], v[140:141], v[156:157]
	v_cvt_pk_bf16_f32 v216, v202, v203
	v_cvt_pk_bf16_f32 v217, v204, v205
	global_store_dwordx2 v[248:249], v[216:217], off offset:32
	global_store_dwordx4 v[246:247], v[26:29], off offset:512
	v_pk_mul_f32 v[198:199], v[26:27], v[194:195] op_sel_hi:[1,0]
	v_pk_fma_f32 v[198:199], v[198:199], v[142:143], v[158:159]
	v_pk_mul_f32 v[200:201], v[28:29], v[194:195] op_sel_hi:[1,0]
	v_pk_fma_f32 v[200:201], v[200:201], v[144:145], v[160:161]
	v_cvt_pk_bf16_f32 v214, v198, v199
	v_cvt_pk_bf16_f32 v215, v200, v201
	global_store_dwordx2 v[248:249], v[214:215], off offset:256
	global_store_dwordx4 v[246:247], v[22:25], off offset:576
	v_pk_mul_f32 v[202:203], v[22:23], v[194:195] op_sel_hi:[1,0]
	v_pk_fma_f32 v[202:203], v[202:203], v[146:147], v[162:163]
	v_pk_mul_f32 v[204:205], v[24:25], v[194:195] op_sel_hi:[1,0]
	v_pk_fma_f32 v[204:205], v[204:205], v[148:149], v[164:165]
	v_cvt_pk_bf16_f32 v216, v202, v203
	v_cvt_pk_bf16_f32 v217, v204, v205
	global_store_dwordx2 v[248:249], v[216:217], off offset:288
	s_mov_b32 s30, 0xb0000
	v_lshl_add_u64 v[246:247], v[242:243], 0, s[30:31]
	s_mov_b32 s30, 0x58000
	v_lshl_add_u64 v[248:249], v[244:245], 0, s[30:31]
	global_store_dwordx4 v[246:247], v[18:21], off offset:0
	v_pk_mul_f32 v[198:199], v[18:19], v[196:197] op_sel_hi:[1,0]
	v_pk_fma_f32 v[198:199], v[198:199], v[134:135], v[150:151]
	v_pk_mul_f32 v[200:201], v[20:21], v[196:197] op_sel_hi:[1,0]
	v_pk_fma_f32 v[200:201], v[200:201], v[136:137], v[152:153]
	v_cvt_pk_bf16_f32 v214, v198, v199
	v_cvt_pk_bf16_f32 v215, v200, v201
	global_store_dwordx2 v[248:249], v[214:215], off offset:0
	global_store_dwordx4 v[246:247], v[14:17], off offset:64
	v_pk_mul_f32 v[202:203], v[14:15], v[196:197] op_sel_hi:[1,0]
	v_pk_fma_f32 v[202:203], v[202:203], v[138:139], v[154:155]
	v_pk_mul_f32 v[204:205], v[16:17], v[196:197] op_sel_hi:[1,0]
	v_pk_fma_f32 v[204:205], v[204:205], v[140:141], v[156:157]
	v_cvt_pk_bf16_f32 v216, v202, v203
	v_cvt_pk_bf16_f32 v217, v204, v205
	global_store_dwordx2 v[248:249], v[216:217], off offset:32
	global_store_dwordx4 v[246:247], v[10:13], off offset:512
	v_pk_mul_f32 v[198:199], v[10:11], v[196:197] op_sel_hi:[1,0]
	v_pk_fma_f32 v[198:199], v[198:199], v[142:143], v[158:159]
	v_pk_mul_f32 v[200:201], v[12:13], v[196:197] op_sel_hi:[1,0]
	v_pk_fma_f32 v[200:201], v[200:201], v[144:145], v[160:161]
	v_cvt_pk_bf16_f32 v214, v198, v199
	v_cvt_pk_bf16_f32 v215, v200, v201
	global_store_dwordx2 v[248:249], v[214:215], off offset:256
	global_store_dwordx4 v[246:247], v[6:9], off offset:576
	v_pk_mul_f32 v[202:203], v[6:7], v[196:197] op_sel_hi:[1,0]
	v_pk_fma_f32 v[202:203], v[202:203], v[146:147], v[162:163]
	v_pk_mul_f32 v[204:205], v[8:9], v[196:197] op_sel_hi:[1,0]
	v_pk_fma_f32 v[204:205], v[204:205], v[148:149], v[164:165]
	v_cvt_pk_bf16_f32 v216, v202, v203
	v_cvt_pk_bf16_f32 v217, v204, v205
	global_store_dwordx2 v[248:249], v[216:217], off offset:288
	s_branch .Lrn_out_done
.Lrn_final_out:
	s_mov_b32 s30, 0x0
	v_lshl_add_u64 v[246:247], v[242:243], 0, s[30:31]
	v_pk_mul_f32 v[198:199], v[130:131], v[182:183] op_sel_hi:[1,0]
	v_pk_mul_f32 v[198:199], v[198:199], v[134:135]
	v_pk_mul_f32 v[200:201], v[132:133], v[182:183] op_sel_hi:[1,0]
	v_pk_mul_f32 v[200:201], v[200:201], v[136:137]
	global_store_dwordx4 v[246:247], v[198:201], off offset:0
	v_pk_mul_f32 v[202:203], v[126:127], v[182:183] op_sel_hi:[1,0]
	v_pk_mul_f32 v[202:203], v[202:203], v[138:139]
	v_pk_mul_f32 v[204:205], v[128:129], v[182:183] op_sel_hi:[1,0]
	v_pk_mul_f32 v[204:205], v[204:205], v[140:141]
	global_store_dwordx4 v[246:247], v[202:205], off offset:64
	v_pk_mul_f32 v[198:199], v[122:123], v[182:183] op_sel_hi:[1,0]
	v_pk_mul_f32 v[198:199], v[198:199], v[142:143]
	v_pk_mul_f32 v[200:201], v[124:125], v[182:183] op_sel_hi:[1,0]
	v_pk_mul_f32 v[200:201], v[200:201], v[144:145]
	global_store_dwordx4 v[246:247], v[198:201], off offset:512
	v_pk_mul_f32 v[202:203], v[118:119], v[182:183] op_sel_hi:[1,0]
	v_pk_mul_f32 v[202:203], v[202:203], v[146:147]
	v_pk_mul_f32 v[204:205], v[120:121], v[182:183] op_sel_hi:[1,0]
	v_pk_mul_f32 v[204:205], v[204:205], v[148:149]
	global_store_dwordx4 v[246:247], v[202:205], off offset:576
	s_mov_b32 s30, 0x10000
	v_lshl_add_u64 v[246:247], v[242:243], 0, s[30:31]
	v_pk_mul_f32 v[198:199], v[114:115], v[184:185] op_sel_hi:[1,0]
	v_pk_mul_f32 v[198:199], v[198:199], v[134:135]
	v_pk_mul_f32 v[200:201], v[116:117], v[184:185] op_sel_hi:[1,0]
	v_pk_mul_f32 v[200:201], v[200:201], v[136:137]
	global_store_dwordx4 v[246:247], v[198:201], off offset:0
	v_pk_mul_f32 v[202:203], v[110:111], v[184:185] op_sel_hi:[1,0]
	v_pk_mul_f32 v[202:203], v[202:203], v[138:139]
	v_pk_mul_f32 v[204:205], v[112:113], v[184:185] op_sel_hi:[1,0]
	v_pk_mul_f32 v[204:205], v[204:205], v[140:141]
	global_store_dwordx4 v[246:247], v[202:205], off offset:64
	v_pk_mul_f32 v[198:199], v[106:107], v[184:185] op_sel_hi:[1,0]
	v_pk_mul_f32 v[198:199], v[198:199], v[142:143]
	v_pk_mul_f32 v[200:201], v[108:109], v[184:185] op_sel_hi:[1,0]
	v_pk_mul_f32 v[200:201], v[200:201], v[144:145]
	global_store_dwordx4 v[246:247], v[198:201], off offset:512
	v_pk_mul_f32 v[202:203], v[102:103], v[184:185] op_sel_hi:[1,0]
	v_pk_mul_f32 v[202:203], v[202:203], v[146:147]
	v_pk_mul_f32 v[204:205], v[104:105], v[184:185] op_sel_hi:[1,0]
	v_pk_mul_f32 v[204:205], v[204:205], v[148:149]
	global_store_dwordx4 v[246:247], v[202:205], off offset:576
	s_mov_b32 s30, 0x20000
	v_lshl_add_u64 v[246:247], v[242:243], 0, s[30:31]
	v_pk_mul_f32 v[198:199], v[98:99], v[186:187] op_sel_hi:[1,0]
	v_pk_mul_f32 v[198:199], v[198:199], v[134:135]
	v_pk_mul_f32 v[200:201], v[100:101], v[186:187] op_sel_hi:[1,0]
	v_pk_mul_f32 v[200:201], v[200:201], v[136:137]
	global_store_dwordx4 v[246:247], v[198:201], off offset:0
	v_pk_mul_f32 v[202:203], v[94:95], v[186:187] op_sel_hi:[1,0]
	v_pk_mul_f32 v[202:203], v[202:203], v[138:139]
	v_pk_mul_f32 v[204:205], v[96:97], v[186:187] op_sel_hi:[1,0]
	v_pk_mul_f32 v[204:205], v[204:205], v[140:141]
	global_store_dwordx4 v[246:247], v[202:205], off offset:64
	v_pk_mul_f32 v[198:199], v[90:91], v[186:187] op_sel_hi:[1,0]
	v_pk_mul_f32 v[198:199], v[198:199], v[142:143]
	v_pk_mul_f32 v[200:201], v[92:93], v[186:187] op_sel_hi:[1,0]
	v_pk_mul_f32 v[200:201], v[200:201], v[144:145]
	global_store_dwordx4 v[246:247], v[198:201], off offset:512
	v_pk_mul_f32 v[202:203], v[86:87], v[186:187] op_sel_hi:[1,0]
	v_pk_mul_f32 v[202:203], v[202:203], v[146:147]
	v_pk_mul_f32 v[204:205], v[88:89], v[186:187] op_sel_hi:[1,0]
	v_pk_mul_f32 v[204:205], v[204:205], v[148:149]
	global_store_dwordx4 v[246:247], v[202:205], off offset:576
	s_mov_b32 s30, 0x30000
	v_lshl_add_u64 v[246:247], v[242:243], 0, s[30:31]
	v_pk_mul_f32 v[198:199], v[82:83], v[188:189] op_sel_hi:[1,0]
	v_pk_mul_f32 v[198:199], v[198:199], v[134:135]
	v_pk_mul_f32 v[200:201], v[84:85], v[188:189] op_sel_hi:[1,0]
	v_pk_mul_f32 v[200:201], v[200:201], v[136:137]
	global_store_dwordx4 v[246:247], v[198:201], off offset:0
	v_pk_mul_f32 v[202:203], v[78:79], v[188:189] op_sel_hi:[1,0]
	v_pk_mul_f32 v[202:203], v[202:203], v[138:139]
	v_pk_mul_f32 v[204:205], v[80:81], v[188:189] op_sel_hi:[1,0]
	v_pk_mul_f32 v[204:205], v[204:205], v[140:141]
	global_store_dwordx4 v[246:247], v[202:205], off offset:64
	v_pk_mul_f32 v[198:199], v[74:75], v[188:189] op_sel_hi:[1,0]
	v_pk_mul_f32 v[198:199], v[198:199], v[142:143]
	v_pk_mul_f32 v[200:201], v[76:77], v[188:189] op_sel_hi:[1,0]
	v_pk_mul_f32 v[200:201], v[200:201], v[144:145]
	global_store_dwordx4 v[246:247], v[198:201], off offset:512
	v_pk_mul_f32 v[202:203], v[70:71], v[188:189] op_sel_hi:[1,0]
	v_pk_mul_f32 v[202:203], v[202:203], v[146:147]
	v_pk_mul_f32 v[204:205], v[72:73], v[188:189] op_sel_hi:[1,0]
	v_pk_mul_f32 v[204:205], v[204:205], v[148:149]
	global_store_dwordx4 v[246:247], v[202:205], off offset:576
	s_mov_b32 s30, 0x80000
	v_lshl_add_u64 v[246:247], v[242:243], 0, s[30:31]
	v_pk_mul_f32 v[198:199], v[66:67], v[190:191] op_sel_hi:[1,0]
	v_pk_mul_f32 v[198:199], v[198:199], v[134:135]
	v_pk_mul_f32 v[200:201], v[68:69], v[190:191] op_sel_hi:[1,0]
	v_pk_mul_f32 v[200:201], v[200:201], v[136:137]
	global_store_dwordx4 v[246:247], v[198:201], off offset:0
	v_pk_mul_f32 v[202:203], v[62:63], v[190:191] op_sel_hi:[1,0]
	v_pk_mul_f32 v[202:203], v[202:203], v[138:139]
	v_pk_mul_f32 v[204:205], v[64:65], v[190:191] op_sel_hi:[1,0]
	v_pk_mul_f32 v[204:205], v[204:205], v[140:141]
	global_store_dwordx4 v[246:247], v[202:205], off offset:64
	v_pk_mul_f32 v[198:199], v[58:59], v[190:191] op_sel_hi:[1,0]
	v_pk_mul_f32 v[198:199], v[198:199], v[142:143]
	v_pk_mul_f32 v[200:201], v[60:61], v[190:191] op_sel_hi:[1,0]
	v_pk_mul_f32 v[200:201], v[200:201], v[144:145]
	global_store_dwordx4 v[246:247], v[198:201], off offset:512
	v_pk_mul_f32 v[202:203], v[54:55], v[190:191] op_sel_hi:[1,0]
	v_pk_mul_f32 v[202:203], v[202:203], v[146:147]
	v_pk_mul_f32 v[204:205], v[56:57], v[190:191] op_sel_hi:[1,0]
	v_pk_mul_f32 v[204:205], v[204:205], v[148:149]
	global_store_dwordx4 v[246:247], v[202:205], off offset:576
	s_mov_b32 s30, 0x90000
	v_lshl_add_u64 v[246:247], v[242:243], 0, s[30:31]
	v_pk_mul_f32 v[198:199], v[50:51], v[192:193] op_sel_hi:[1,0]
	v_pk_mul_f32 v[198:199], v[198:199], v[134:135]
	v_pk_mul_f32 v[200:201], v[52:53], v[192:193] op_sel_hi:[1,0]
	v_pk_mul_f32 v[200:201], v[200:201], v[136:137]
	global_store_dwordx4 v[246:247], v[198:201], off offset:0
	v_pk_mul_f32 v[202:203], v[46:47], v[192:193] op_sel_hi:[1,0]
	v_pk_mul_f32 v[202:203], v[202:203], v[138:139]
	v_pk_mul_f32 v[204:205], v[48:49], v[192:193] op_sel_hi:[1,0]
	v_pk_mul_f32 v[204:205], v[204:205], v[140:141]
	global_store_dwordx4 v[246:247], v[202:205], off offset:64
	v_pk_mul_f32 v[198:199], v[42:43], v[192:193] op_sel_hi:[1,0]
	v_pk_mul_f32 v[198:199], v[198:199], v[142:143]
	v_pk_mul_f32 v[200:201], v[44:45], v[192:193] op_sel_hi:[1,0]
	v_pk_mul_f32 v[200:201], v[200:201], v[144:145]
	global_store_dwordx4 v[246:247], v[198:201], off offset:512
	v_pk_mul_f32 v[202:203], v[38:39], v[192:193] op_sel_hi:[1,0]
	v_pk_mul_f32 v[202:203], v[202:203], v[146:147]
	v_pk_mul_f32 v[204:205], v[40:41], v[192:193] op_sel_hi:[1,0]
	v_pk_mul_f32 v[204:205], v[204:205], v[148:149]
	global_store_dwordx4 v[246:247], v[202:205], off offset:576
	s_mov_b32 s30, 0xa0000
	v_lshl_add_u64 v[246:247], v[242:243], 0, s[30:31]
	v_pk_mul_f32 v[198:199], v[34:35], v[194:195] op_sel_hi:[1,0]
	v_pk_mul_f32 v[198:199], v[198:199], v[134:135]
	v_pk_mul_f32 v[200:201], v[36:37], v[194:195] op_sel_hi:[1,0]
	v_pk_mul_f32 v[200:201], v[200:201], v[136:137]
	global_store_dwordx4 v[246:247], v[198:201], off offset:0
	v_pk_mul_f32 v[202:203], v[30:31], v[194:195] op_sel_hi:[1,0]
	v_pk_mul_f32 v[202:203], v[202:203], v[138:139]
	v_pk_mul_f32 v[204:205], v[32:33], v[194:195] op_sel_hi:[1,0]
	v_pk_mul_f32 v[204:205], v[204:205], v[140:141]
	global_store_dwordx4 v[246:247], v[202:205], off offset:64
	v_pk_mul_f32 v[198:199], v[26:27], v[194:195] op_sel_hi:[1,0]
	v_pk_mul_f32 v[198:199], v[198:199], v[142:143]
	v_pk_mul_f32 v[200:201], v[28:29], v[194:195] op_sel_hi:[1,0]
	v_pk_mul_f32 v[200:201], v[200:201], v[144:145]
	global_store_dwordx4 v[246:247], v[198:201], off offset:512
	v_pk_mul_f32 v[202:203], v[22:23], v[194:195] op_sel_hi:[1,0]
	v_pk_mul_f32 v[202:203], v[202:203], v[146:147]
	v_pk_mul_f32 v[204:205], v[24:25], v[194:195] op_sel_hi:[1,0]
	v_pk_mul_f32 v[204:205], v[204:205], v[148:149]
	global_store_dwordx4 v[246:247], v[202:205], off offset:576
	s_mov_b32 s30, 0xb0000
	v_lshl_add_u64 v[246:247], v[242:243], 0, s[30:31]
	v_pk_mul_f32 v[198:199], v[18:19], v[196:197] op_sel_hi:[1,0]
	v_pk_mul_f32 v[198:199], v[198:199], v[134:135]
	v_pk_mul_f32 v[200:201], v[20:21], v[196:197] op_sel_hi:[1,0]
	v_pk_mul_f32 v[200:201], v[200:201], v[136:137]
	global_store_dwordx4 v[246:247], v[198:201], off offset:0
	v_pk_mul_f32 v[202:203], v[14:15], v[196:197] op_sel_hi:[1,0]
	v_pk_mul_f32 v[202:203], v[202:203], v[138:139]
	v_pk_mul_f32 v[204:205], v[16:17], v[196:197] op_sel_hi:[1,0]
	v_pk_mul_f32 v[204:205], v[204:205], v[140:141]
	global_store_dwordx4 v[246:247], v[202:205], off offset:64
	v_pk_mul_f32 v[198:199], v[10:11], v[196:197] op_sel_hi:[1,0]
	v_pk_mul_f32 v[198:199], v[198:199], v[142:143]
	v_pk_mul_f32 v[200:201], v[12:13], v[196:197] op_sel_hi:[1,0]
	v_pk_mul_f32 v[200:201], v[200:201], v[144:145]
	global_store_dwordx4 v[246:247], v[198:201], off offset:512
	v_pk_mul_f32 v[202:203], v[6:7], v[196:197] op_sel_hi:[1,0]
	v_pk_mul_f32 v[202:203], v[202:203], v[146:147]
	v_pk_mul_f32 v[204:205], v[8:9], v[196:197] op_sel_hi:[1,0]
	v_pk_mul_f32 v[204:205], v[204:205], v[148:149]
	global_store_dwordx4 v[246:247], v[202:205], off offset:576
.Lrn_out_done:
	s_and_b64 vcc, exec, s[2:3]
	s_mov_b64 s[2:3], -1
	s_cbranch_vccnz .LBB0_279
.LBB0_309:
	s_andn2_b64 vcc, exec, s[16:17]
	s_cbranch_vccnz .LBB0_278
	s_barrier
	s_branch .LBB0_278

.LBB0_604:
	v_readlane_b32 s2, v252, 3
	s_cmp_lg_u32 s2, 2
	s_cbranch_scc1 .LBB0_630
	s_abs_i32 s2, s70
	v_cvt_f32_u32_e32 v2, s2
	s_sub_i32 s3, s70, s58
	s_add_i32 s5, s3, 0x3fff
	s_sub_i32 s3, 0xffffc001, s3
	v_rcp_iflag_f32_e32 v2, v2
	s_xor_b32 s14, s5, s70
	s_sub_i32 s7, 0, s2
	s_max_i32 s3, s5, s3
	v_mul_f32_e32 v2, 0x4f7ffffe, v2
	v_cvt_u32_f32_e32 v2, v2
	s_ashr_i32 s5, s14, 31
	v_readfirstlane_b32 s14, v2
	s_mul_i32 s7, s7, s14
	s_mul_hi_u32 s7, s14, s7
	s_add_i32 s14, s14, s7
	s_mul_hi_u32 s7, s3, s14
	s_mul_i32 s14, s7, s2
	s_sub_i32 s3, s3, s14
	s_add_i32 s15, s7, 1
	s_sub_i32 s14, s3, s2
	s_cmp_ge_u32 s3, s2
	s_cselect_b32 s7, s15, s7
	s_cselect_b32 s3, s14, s3
	s_add_i32 s14, s7, 1
	s_cmp_ge_u32 s3, s2
	s_cselect_b32 s2, s14, s7
	s_xor_b32 s2, s2, s5
	s_sub_i32 s5, s2, s5
	s_cmpk_eq_i32 s40, 0x100
	s_cselect_b64 s[2:3], -1, 0
	s_and_b64 s[14:15], s[2:3], exec
	s_cselect_b32 s18, s4, s5
	s_cmp_lt_i32 s18, 1
	s_cbranch_scc1 .LBB0_630
	v_and_b32_e32 v2, 64, v238
	v_add_u32_e32 v2, 64, v2
	v_xor_b32_e32 v3, 1, v238
	v_cmp_lt_i32_e32 vcc, v3, v2
	s_add_i32 s7, s58, 0x1400
	s_and_b64 s[4:5], s[12:13], exec
	v_cndmask_b32_e32 v3, v238, v3, vcc
	v_lshlrev_b32_e32 v124, 2, v3
	v_xor_b32_e32 v3, 2, v238
	v_cmp_lt_i32_e32 vcc, v3, v2
	s_cselect_b32 s4, s58, s7
	s_and_b64 s[2:3], s[2:3], exec
	v_cndmask_b32_e32 v3, v238, v3, vcc
	v_lshlrev_b32_e32 v125, 2, v3
	v_xor_b32_e32 v3, 4, v238
	v_cmp_lt_i32_e32 vcc, v3, v2
	s_cselect_b32 s12, s4, s58
	s_cselect_b32 s19, 0x400, s70
	v_cndmask_b32_e32 v3, v238, v3, vcc
	v_lshlrev_b32_e32 v126, 2, v3
	v_xor_b32_e32 v3, 8, v238
	v_cmp_lt_i32_e32 vcc, v3, v2
	s_ashr_i32 s7, s6, 31
	s_lshl_b64 s[2:3], s[6:7], 2
	v_cndmask_b32_e32 v3, v238, v3, vcc
	v_lshlrev_b32_e32 v127, 2, v3
	v_xor_b32_e32 v3, 16, v238
	v_cmp_lt_i32_e32 vcc, v3, v2
	s_add_u32 s2, s72, s2
	s_addc_u32 s3, s73, s3
	v_cndmask_b32_e32 v3, v238, v3, vcc
	v_lshlrev_b32_e32 v128, 2, v3
	v_xor_b32_e32 v3, 32, v238
	s_cmp_eq_u32 s28, 0
	v_cmp_lt_i32_e32 vcc, v3, v2
	s_cselect_b32 s4, 0, 0x3000
	s_add_u32 s21, s2, s4
	v_cndmask_b32_e32 v2, v238, v3, vcc
	v_lshlrev_b32_e32 v129, 2, v2
	v_lshlrev_b32_e32 v2, 3, v233
	v_mov_b32_e32 v3, v1
	s_mov_b32 s20, 0
	s_addc_u32 s22, s3, 0
	v_lshl_add_u64 v[2:3], s[80:81], 0, v[2:3]
	s_waitcnt lgkmcnt(0)
	v_lshl_add_u64 v[118:119], s[8:9], 0, v[0:1]
	s_lshl_b32 s23, s19, 1
	s_branch .LBB0_607
